# hoist LDS reads ahead of MFMA chains in GLA item phases P2/P4 (fresh regs, counted lgkmcnt), V^T reads hoisted above softmax in attention
# speedup vs baseline: 1.0203x; 1.0082x over previous
; #define LAS __attribute__((address_space(3)))
; #define MFMA32(a, b, c) __builtin_amdgcn_mfma_f32_32x32x16_bf16((a), (b), (c), 0, 0, 0)
; template <int MODE> __device__ __forceinline__ void gla_item(const Args& a, LAS unsigned char* lds, int cid, int h, GlaPre& pf, int next) {
;     ...
;         bf16x8 vf[4];
; #pragma unroll
;         for (int ks = 0; ks < 4; ++ks) vf[ks] = *(const LAS bf16x8*)(VT + (32 * w + l31) * VTS + 16 * ks + 8 * hi);
;         f32x16 acc[4];
; #pragma unroll
;         for (int d = 0; d < 4; ++d) acc[d] = f32x16{};
; #pragma unroll
;         for (int d = 0; d < 4; ++d)
; #pragma unroll
;             for (int ks = 0; ks < 4; ++ks) { const bf16x8 kf = *(const LAS bf16x8*)(KDT + (32 * d + l31) * VTS + 16 * ks + 8 * hi);
;                 acc[d] = prompt ? MFMA32(vf[ks], kf, acc[d]) : MFMA32(kf, vf[ks], acc[d]); }
.LBB0_463:
	s_or_b64 exec, exec, s[0:1]
	s_ashr_i32 s1, s88, 1
	v_bfe_u32 v71, v20, 5, 1
	v_mov_b32_e32 v2, s1
	v_and_b32_e32 v72, 31, v20
	v_bfi_b32 v2, s86, v2, v20
	v_lshl_add_u32 v6, v71, 4, 0
	v_mad_u64_u32 v[8:9], s[72:73], v2, s77, v[6:7]
	v_mad_u32_u24 v77, v72, s77, v6
	s_waitcnt lgkmcnt(0)
	s_barrier
	ds_read_b128 v[170:173], v8 offset:43008
	ds_read_b128 v[174:177], v8 offset:43040
	ds_read_b128 v[178:181], v8 offset:43072
	ds_read_b128 v[182:185], v8 offset:43104
	ds_read_b128 v[186:189], v77 offset:8192
	ds_read_b128 v[190:193], v77 offset:8224
	ds_read_b128 v[194:197], v77 offset:8256
	ds_read_b128 v[198:201], v77 offset:22048
	ds_read_b128 v[202:205], v77 offset:8288
	ds_read_b128 v[206:209], v77 offset:12800
	ds_read_b128 v[210:213], v77 offset:12832
	ds_read_b128 v[214:217], v77 offset:12864
	ds_read_b128 v[218:221], v77 offset:12896
	ds_read_b128 v[222:225], v77 offset:17408
	s_waitcnt lgkmcnt(9)
	ds_read_b128 v[226:229], v77 offset:17440
	ds_read_b128 v[230:233], v77 offset:17472
	ds_read_b128 v[234:237], v77 offset:17504
	ds_read_b128 v[238:241], v77 offset:22016
	ds_read_b128 v[242:245], v77 offset:22080
	v_mfma_f32_32x32x16_bf16 v[50:65], v[170:173], v[186:189], 0
	s_and_b32 s0, s1, 0xffffffe0
	s_ashr_i32 s1, s0, 31
	v_lshlrev_b64 v[74:75], 16, v[74:75]
	v_lshl_add_u64 v[74:75], s[6:7], 0, v[74:75]
	s_lshl_b64 s[0:1], s[0:1], 8
	s_waitcnt lgkmcnt(13)
	ds_read_b128 v[246:249], v77 offset:22112
	v_mfma_f32_32x32x16_bf16 v[50:65], v[174:177], v[190:193], v[50:65]
	v_lshl_add_u64 v[74:75], v[74:75], 0, s[0:1]
	v_lshlrev_b32_e32 v72, 1, v72
	s_add_u32 s8, s8, 0x20000
	s_addc_u32 s9, s9, 0
	s_addk_i32 s3, 0x1000
	s_add_i32 s53, s53, 0x8000
	s_add_i32 s0, s70, 0xffffff00
	s_waitcnt lgkmcnt(13)
	v_mfma_f32_32x32x16_bf16 v[50:65], v[178:181], v[194:197], v[50:65]
	s_cmpk_gt_i32 s0, 0x2ff
	s_waitcnt lgkmcnt(11)
	v_mfma_f32_32x32x16_bf16 v[50:65], v[182:185], v[202:205], v[50:65]
	s_waitcnt lgkmcnt(10)
	v_mfma_f32_32x32x16_bf16 v[34:49], v[170:173], v[206:209], 0
	s_waitcnt lgkmcnt(9)
	v_mfma_f32_32x32x16_bf16 v[34:49], v[174:177], v[210:213], v[34:49]
	s_waitcnt lgkmcnt(8)
	v_mfma_f32_32x32x16_bf16 v[34:49], v[178:181], v[214:217], v[34:49]
	s_waitcnt lgkmcnt(7)
	v_mfma_f32_32x32x16_bf16 v[34:49], v[182:185], v[218:221], v[34:49]
	s_waitcnt lgkmcnt(6)
	v_mfma_f32_32x32x16_bf16 v[18:33], v[170:173], v[222:225], 0
	s_waitcnt lgkmcnt(5)
	v_mfma_f32_32x32x16_bf16 v[18:33], v[174:177], v[226:229], v[18:33]
	s_waitcnt lgkmcnt(4)
	v_mfma_f32_32x32x16_bf16 v[18:33], v[178:181], v[230:233], v[18:33]
	s_waitcnt lgkmcnt(3)
	v_mfma_f32_32x32x16_bf16 v[18:33], v[182:185], v[234:237], v[18:33]
	s_waitcnt lgkmcnt(2)
	v_mfma_f32_32x32x16_bf16 v[2:17], v[170:173], v[238:241], 0
	v_mfma_f32_32x32x16_bf16 v[2:17], v[174:177], v[198:201], v[2:17]
	s_waitcnt lgkmcnt(1)
	v_mfma_f32_32x32x16_bf16 v[2:17], v[178:181], v[242:245], v[2:17]
	s_waitcnt lgkmcnt(0)
	v_mfma_f32_32x32x16_bf16 v[2:17], v[182:185], v[246:249], v[2:17]
	v_lshlrev_b32_e32 v200, 12, v1
	v_add_u32_e32 v200, 0x16000, v200
	v_lshl_add_u32 v201, v71, 9, v200
	v_add_u32_e32 v201, v201, v72
	v_mbcnt_lo_u32_b32 v202, -1, 0
	v_mbcnt_hi_u32_b32 v202, -1, v202
	v_lshrrev_b32_e32 v203, 3, v202
	v_and_b32_e32 v204, 7, v202
	v_lshlrev_b32_e32 v205, 7, v203
	v_lshl_add_u32 v205, v204, 4, v205
	v_add_u32_e32 v205, v200, v205
	v_lshlrev_b32_e32 v206, 8, v203
	v_lshl_add_u32 v206, v204, 4, v206
	v_mov_b32_e32 v207, 0
	v_lshl_add_u64 v[208:209], v[74:75], 0, v[206:207]
	v_add_co_u32_e32 v210, vcc, 0x1000, v208
	s_nop 1
	v_addc_co_u32_e32 v211, vcc, 0, v209, vcc
	v_cvt_pk_bf16_f32 v212, v50, v50
	ds_write_b16 v201, v212
	v_cvt_pk_bf16_f32 v213, v51, v51
	ds_write_b16 v201, v213 offset:128
	v_cvt_pk_bf16_f32 v214, v52, v52
	ds_write_b16 v201, v214 offset:256
	v_cvt_pk_bf16_f32 v215, v53, v53
	ds_write_b16 v201, v215 offset:384
	v_cvt_pk_bf16_f32 v212, v54, v54
	ds_write_b16 v201, v212 offset:1024
	v_cvt_pk_bf16_f32 v213, v55, v55
	ds_write_b16 v201, v213 offset:1152
	v_cvt_pk_bf16_f32 v214, v56, v56
	ds_write_b16 v201, v214 offset:1280
	v_cvt_pk_bf16_f32 v215, v57, v57
	ds_write_b16 v201, v215 offset:1408
	v_cvt_pk_bf16_f32 v212, v58, v58
	ds_write_b16 v201, v212 offset:2048
	v_cvt_pk_bf16_f32 v213, v59, v59
	ds_write_b16 v201, v213 offset:2176
	v_cvt_pk_bf16_f32 v214, v60, v60
	ds_write_b16 v201, v214 offset:2304
	v_cvt_pk_bf16_f32 v215, v61, v61
	ds_write_b16 v201, v215 offset:2432
	v_cvt_pk_bf16_f32 v212, v62, v62
	ds_write_b16 v201, v212 offset:3072
	v_cvt_pk_bf16_f32 v213, v63, v63
	ds_write_b16 v201, v213 offset:3200
	v_cvt_pk_bf16_f32 v214, v64, v64
	ds_write_b16 v201, v214 offset:3328
	v_cvt_pk_bf16_f32 v215, v65, v65
	ds_write_b16 v201, v215 offset:3456
	v_cvt_pk_bf16_f32 v212, v34, v34
	ds_write_b16 v201, v212 offset:64
	v_cvt_pk_bf16_f32 v213, v35, v35
	ds_write_b16 v201, v213 offset:192
	v_cvt_pk_bf16_f32 v214, v36, v36
	ds_write_b16 v201, v214 offset:320
	v_cvt_pk_bf16_f32 v215, v37, v37
	ds_write_b16 v201, v215 offset:448
	v_cvt_pk_bf16_f32 v212, v38, v38
	ds_write_b16 v201, v212 offset:1088
	v_cvt_pk_bf16_f32 v213, v39, v39
	ds_write_b16 v201, v213 offset:1216
	v_cvt_pk_bf16_f32 v214, v40, v40
	ds_write_b16 v201, v214 offset:1344
	v_cvt_pk_bf16_f32 v215, v41, v41
	ds_write_b16 v201, v215 offset:1472
	v_cvt_pk_bf16_f32 v212, v42, v42
	ds_write_b16 v201, v212 offset:2112
	v_cvt_pk_bf16_f32 v213, v43, v43
	ds_write_b16 v201, v213 offset:2240
	v_cvt_pk_bf16_f32 v214, v44, v44
	ds_write_b16 v201, v214 offset:2368
	v_cvt_pk_bf16_f32 v215, v45, v45
	ds_write_b16 v201, v215 offset:2496
	v_cvt_pk_bf16_f32 v212, v46, v46
	ds_write_b16 v201, v212 offset:3136
	v_cvt_pk_bf16_f32 v213, v47, v47
	ds_write_b16 v201, v213 offset:3264
	v_cvt_pk_bf16_f32 v214, v48, v48
	ds_write_b16 v201, v214 offset:3392
	v_cvt_pk_bf16_f32 v215, v49, v49
	ds_write_b16 v201, v215 offset:3520
	s_waitcnt lgkmcnt(0)
; __device__ __forceinline__ unsigned f2bf(float f) { unsigned u = __float_as_uint(f); return (u + 0x7fffu + ((u >> 16) & 1u)) >> 16; }
; __device__ __forceinline__ int crow(int r, int hi) { return (r & 3) + 8 * (r >> 2) + 4 * hi; }
; template <int MODE> __device__ __forceinline__ void gla_item(const Args& a, LAS unsigned char* lds, int cid, int h, GlaPre& pf, int next) {
;     ...
;         if (prompt) {
;             bf16_t* dst = (bf16_t*)(a.ws + WS_DST) + ((size_t)(cid * 4 + h) * 256 + 32 * w) * 128;
; #pragma unroll
;             for (int d = 0; d < 4; ++d)
; #pragma unroll
;                 for (int r = 0; r < 16; ++r) dst[(size_t)crow(r, hi) * 128 + 32 * d + l31] = (bf16_t)f2bf(acc[d][r]);
;     ...
;     __syncthreads();
	ds_read_b128 v[216:219], v205
	ds_read_b128 v[220:223], v205 offset:1024
	ds_read_b128 v[224:227], v205 offset:2048
	ds_read_b128 v[228:231], v205 offset:3072
	s_waitcnt lgkmcnt(0)
	global_store_dwordx4 v[208:209], v[216:219], off
	global_store_dwordx4 v[208:209], v[220:223], off offset:2048
	global_store_dwordx4 v[210:211], v[224:227], off
	global_store_dwordx4 v[210:211], v[228:231], off offset:2048
	s_nop 1
	v_cvt_pk_bf16_f32 v212, v18, v18
	ds_write_b16 v201, v212
	v_cvt_pk_bf16_f32 v213, v19, v19
	ds_write_b16 v201, v213 offset:128
	v_cvt_pk_bf16_f32 v214, v20, v20
	ds_write_b16 v201, v214 offset:256
	v_cvt_pk_bf16_f32 v215, v21, v21
	ds_write_b16 v201, v215 offset:384
	v_cvt_pk_bf16_f32 v212, v22, v22
	ds_write_b16 v201, v212 offset:1024
	v_cvt_pk_bf16_f32 v213, v23, v23
	ds_write_b16 v201, v213 offset:1152
	v_cvt_pk_bf16_f32 v214, v24, v24
	ds_write_b16 v201, v214 offset:1280
	v_cvt_pk_bf16_f32 v215, v25, v25
	ds_write_b16 v201, v215 offset:1408
	v_cvt_pk_bf16_f32 v212, v26, v26
	ds_write_b16 v201, v212 offset:2048
	v_cvt_pk_bf16_f32 v213, v27, v27
	ds_write_b16 v201, v213 offset:2176
	v_cvt_pk_bf16_f32 v214, v28, v28
	ds_write_b16 v201, v214 offset:2304
	v_cvt_pk_bf16_f32 v215, v29, v29
	ds_write_b16 v201, v215 offset:2432
	v_cvt_pk_bf16_f32 v212, v30, v30
	ds_write_b16 v201, v212 offset:3072
	v_cvt_pk_bf16_f32 v213, v31, v31
	ds_write_b16 v201, v213 offset:3200
	v_cvt_pk_bf16_f32 v214, v32, v32
	ds_write_b16 v201, v214 offset:3328
	v_cvt_pk_bf16_f32 v215, v33, v33
	ds_write_b16 v201, v215 offset:3456
	v_cvt_pk_bf16_f32 v212, v2, v2
	ds_write_b16 v201, v212 offset:64
	v_cvt_pk_bf16_f32 v213, v3, v3
	ds_write_b16 v201, v213 offset:192
	v_cvt_pk_bf16_f32 v214, v4, v4
	ds_write_b16 v201, v214 offset:320
	v_cvt_pk_bf16_f32 v215, v5, v5
	ds_write_b16 v201, v215 offset:448
	v_cvt_pk_bf16_f32 v212, v6, v6
	ds_write_b16 v201, v212 offset:1088
	v_cvt_pk_bf16_f32 v213, v7, v7
	ds_write_b16 v201, v213 offset:1216
	v_cvt_pk_bf16_f32 v214, v8, v8
	ds_write_b16 v201, v214 offset:1344
	v_cvt_pk_bf16_f32 v215, v9, v9
	ds_write_b16 v201, v215 offset:1472
	v_cvt_pk_bf16_f32 v212, v10, v10
	ds_write_b16 v201, v212 offset:2112
	v_cvt_pk_bf16_f32 v213, v11, v11
	ds_write_b16 v201, v213 offset:2240
	v_cvt_pk_bf16_f32 v214, v12, v12
	ds_write_b16 v201, v214 offset:2368
	v_cvt_pk_bf16_f32 v215, v13, v13
	ds_write_b16 v201, v215 offset:2496
	v_cvt_pk_bf16_f32 v212, v14, v14
	ds_write_b16 v201, v212 offset:3136
	v_cvt_pk_bf16_f32 v213, v15, v15
	ds_write_b16 v201, v213 offset:3264
	v_cvt_pk_bf16_f32 v214, v16, v16
	ds_write_b16 v201, v214 offset:3392
	v_cvt_pk_bf16_f32 v215, v17, v17
	ds_write_b16 v201, v215 offset:3520
	s_waitcnt lgkmcnt(0)
	ds_read_b128 v[216:219], v205
	ds_read_b128 v[220:223], v205 offset:1024
	ds_read_b128 v[224:227], v205 offset:2048
	ds_read_b128 v[228:231], v205 offset:3072
	s_waitcnt lgkmcnt(0)
	global_store_dwordx4 v[208:209], v[216:219], off offset:128
	global_store_dwordx4 v[208:209], v[220:223], off offset:2176
	global_store_dwordx4 v[210:211], v[224:227], off offset:128
	global_store_dwordx4 v[210:211], v[228:231], off offset:2176
	s_nop 1
	s_waitcnt vmcnt(63) expcnt(7) lgkmcnt(15)
	s_barrier
	s_cbranch_scc1 .LBB0_465
	s_mov_b64 s[72:73], s[70:71]
	s_branch .LBB0_457

; #define LAS __attribute__((address_space(3)))
; __device__ __forceinline__ float bf2f(unsigned u) { return __uint_as_float(u << 16); }
; __device__ __forceinline__ unsigned pk(float lo, float hi) { return pg8::cvt_pk_bf16(lo, hi); }
; __device__ __forceinline__ int crow(int r, int hi) { return (r & 3) + 8 * (r >> 2) + 4 * hi; }
; __device__ __forceinline__ float dot4(f32x4 v) { return (v[0] * v[0] + v[1] * v[1]) + (v[2] * v[2] + v[3] * v[3]); }
; #define MFMA32(a, b, c) __builtin_amdgcn_mfma_f32_32x32x16_bf16((a), (b), (c), 0, 0, 0)
; template <int MODE> __device__ __forceinline__ void gla_item(const Args& a, LAS unsigned char* lds, int cid, int h, GlaPre& pf, int next) {
;     ...
;         __syncthreads();
; #pragma unroll
;         for (int tb = 0; tb < 2; ++tb)
; #pragma unroll
;             for (int ks = 0; ks < 4; ++ks) { if (tb == 0 && ks >= 2) continue;
;                 const bf16x8 aa = *(const LAS bf16x8*)(AL + (32 * tb + l31) * VTS + 16 * ks + 8 * hi), vb = *(const LAS bf16x8*)(VT + (32 * w + l31) * VTS + 16 * ks + 8 * hi);
;                 o[tb] = MFMA32(aa, vb, o[tb]); }
;         __syncthreads();
;         LAS float* OL = (LAS float*)(lds + OL_OFF);
; #pragma unroll
;         for (int tb = 0; tb < 2; ++tb)
; #pragma unroll
;             for (int r = 0; r < 16; ++r) OL[(32 * tb + crow(r, hi)) * OLS + 32 * w + l31] = o[tb][r];
;         __syncthreads();
;         const f32x4 ng = *(const f32x4*)(a.in[I_GNORM] + h * 256 + 4 * lane);
;         bf16_t* OG = (bf16_t*)(a.ws + WS_OG);
; #pragma unroll
;         for (int i = 0; i < 8; ++i) { const int t = 8 * w + i; const f32x4 v = *(const LAS f32x4*)(OL + t * OLS + 4 * lane);
;             const float rs = rsqrtf(wave_sum(dot4(v)) * (1.f / 256.f) + EPS);
;             const u32x2 rr = rraw[i];
;             float rv[4] = {bf2f(rr.x & 0xffffu), bf2f(rr.x >> 16), bf2f(rr.y & 0xffffu), bf2f(rr.y >> 16)}; float y[4];
; #pragma unroll
;             for (int j = 0; j < 4; ++j) y[j] = v[j] * rs * ng[j] * rv[j] * __builtin_amdgcn_rcpf(1.f + __expf(-rv[j]));
;             u32x2 ov; ov.x = pk(y[0], y[1]); ov.y = pk(y[2], y[3]);
;             *(u32x2*)(OG + (size_t)(row0 + t) * DM + h * 256 + 4 * lane) = ov; }
.LBB0_699:
	v_lshl_or_b32 v35, s86, 5, v74
	v_lshlrev_b32_e32 v34, 1, v34
	v_mul_lo_u32 v35, v35, s77
	s_add_i32 s0, 0, 0x13800
	v_add3_u32 v63, 0, v35, v34
	v_mul_u32_u24_e32 v35, 0x90, v74
	v_add3_u32 v64, s0, v34, v35
	s_waitcnt lgkmcnt(0)
	s_barrier
	ds_read_b128 v[170:173], v64
	ds_read_b128 v[174:177], v64 offset:32
	ds_read_b128 v[178:181], v63 offset:43008
	ds_read_b128 v[182:185], v63 offset:43040
	ds_read_b128 v[186:189], v64 offset:4608
	ds_read_b128 v[190:193], v64 offset:4640
	ds_read_b128 v[194:197], v64 offset:4672
	ds_read_b128 v[198:201], v63 offset:43072
	ds_read_b128 v[202:205], v64 offset:4704
	ds_read_b128 v[206:209], v63 offset:43104
	s_waitcnt lgkmcnt(7)
	v_mfma_f32_32x32x16_bf16 v[2:17], v[170:173], v[178:181], v[2:17]
	s_lshl_b32 s0, s86, 7
	s_add_i32 s0, s0, 0
	v_lshlrev_b32_e32 v62, 2, v123
	s_mulk_i32 s86, 0x2080
	v_lshlrev_b32_e32 v66, 1, v62
	s_waitcnt lgkmcnt(5)
	v_mfma_f32_32x32x16_bf16 v[18:33], v[186:189], v[178:181], v[18:33]
	s_waitcnt lgkmcnt(4)
	v_mfma_f32_32x32x16_bf16 v[18:33], v[190:193], v[182:185], v[18:33]
	v_mfma_f32_32x32x16_bf16 v[2:17], v[174:177], v[182:185], v[2:17]
	s_waitcnt lgkmcnt(2)
	v_mfma_f32_32x32x16_bf16 v[18:33], v[194:197], v[198:201], v[18:33]
	s_waitcnt lgkmcnt(0)
	s_barrier
	v_mfma_f32_32x32x16_bf16 v[18:33], v[202:205], v[206:209], v[18:33]
	v_mul_u32_u24_e32 v34, 0x1040, v122
	v_add3_u32 v34, s0, v72, v34
	s_lshl_b32 s0, s8, 2
	s_add_u32 s0, s40, s0
	v_add_u32_e32 v35, 0x2000, v34
	ds_write_b32 v34, v2 offset:8192
	ds_write_b32 v34, v3 offset:9232
	ds_write_b32 v34, v4 offset:10272
	ds_write_b32 v34, v5 offset:11312
	ds_write_b32 v34, v6 offset:16512
	ds_write_b32 v34, v7 offset:17552
	ds_write_b32 v34, v8 offset:18592
	ds_write_b32 v34, v9 offset:19632
	ds_write_b32 v34, v10 offset:24832
	ds_write_b32 v34, v11 offset:25872
	ds_write_b32 v34, v12 offset:26912
	ds_write_b32 v34, v13 offset:27952
	ds_write_b32 v34, v14 offset:33152
	ds_write_b32 v34, v15 offset:34192
	ds_write_b32 v34, v16 offset:35232
	ds_write_b32 v34, v17 offset:36272
	ds_write_b32 v34, v18 offset:41472
	ds_write_b32 v34, v19 offset:42512
	ds_write_b32 v34, v20 offset:43552
	ds_write_b32 v34, v21 offset:44592
	ds_write_b32 v34, v22 offset:49792
	ds_write_b32 v34, v23 offset:50832
	ds_write_b32 v34, v24 offset:51872
	ds_write_b32 v34, v25 offset:52912
	ds_write_b32 v34, v26 offset:58112
	ds_write_b32 v34, v27 offset:59152
	ds_write_b32 v34, v28 offset:60192
	ds_write_b32 v34, v29 offset:61232
	ds_write_b32 v35, v30 offset:58240
	ds_write_b32 v35, v31 offset:59280
	ds_write_b32 v35, v32 offset:60320
	ds_write_b32 v35, v33 offset:61360
	s_addc_u32 s1, s41, 0
	v_lshlrev_b32_e32 v6, 2, v62
	s_waitcnt lgkmcnt(0)
	s_barrier
	global_load_dwordx4 v[2:5], v6, s[0:1]
	v_add_u32_e32 v11, 0, v6
	v_add_u32_e32 v15, s86, v11
	ds_read_b128 v[16:19], v15 offset:8192
	v_and_b32_e32 v6, 64, v95
	v_add_u32_e32 v6, 64, v6
	v_xor_b32_e32 v7, 1, v95
	v_cmp_lt_i32_e32 vcc, v7, v6
	s_waitcnt lgkmcnt(0)
	v_pk_mul_f32 v[20:21], v[18:19], v[18:19]
	v_pk_mul_f32 v[22:23], v[16:17], v[16:17]
	v_cndmask_b32_e32 v7, v95, v7, vcc
	v_pk_mov_b32 v[24:25], v[22:23], v[20:21] op_sel:[1,0]
	v_mov_b32_e32 v23, v21
	v_pk_add_f32 v[20:21], v[24:25], v[22:23]
	v_lshlrev_b32_e32 v8, 2, v7
	v_add_f32_e32 v15, v20, v21
	ds_bpermute_b32 v20, v8, v15
	v_xor_b32_e32 v7, 2, v95
	v_cmp_lt_i32_e32 vcc, v7, v6
	s_waitcnt vmcnt(8)
	v_and_b32_e32 v21, 0xffff0000, v84
	v_lshlrev_b32_e32 v22, 16, v85
	v_cndmask_b32_e32 v7, v95, v7, vcc
	v_lshlrev_b32_e32 v9, 2, v7
	s_waitcnt lgkmcnt(0)
	v_add_f32_e32 v15, v15, v20
	ds_bpermute_b32 v20, v9, v15
	v_xor_b32_e32 v7, 4, v95
	v_cmp_lt_i32_e32 vcc, v7, v6
	v_and_b32_e32 v23, 0xffff0000, v85
	s_lshl_b32 s0, s8, 1
	v_cndmask_b32_e32 v7, v95, v7, vcc
	v_lshlrev_b32_e32 v10, 2, v7
	s_waitcnt lgkmcnt(0)
	v_add_f32_e32 v15, v15, v20
	ds_bpermute_b32 v20, v10, v15
	v_xor_b32_e32 v7, 8, v95
	v_cmp_lt_i32_e32 vcc, v7, v6
	s_add_u32 s0, s60, s0
	s_addc_u32 s1, s61, 0
	v_cndmask_b32_e32 v7, v95, v7, vcc
	v_lshlrev_b32_e32 v12, 2, v7
	s_waitcnt lgkmcnt(0)
	v_add_f32_e32 v15, v15, v20
	ds_bpermute_b32 v20, v12, v15
	v_xor_b32_e32 v7, 16, v95
	v_cmp_lt_i32_e32 vcc, v7, v6
	s_add_i32 s56, s56, s85
	s_add_i32 s54, s54, s85
	v_cndmask_b32_e32 v7, v95, v7, vcc
	v_lshlrev_b32_e32 v13, 2, v7
	s_waitcnt lgkmcnt(0)
	v_add_f32_e32 v15, v15, v20
	ds_bpermute_b32 v20, v13, v15
	v_xor_b32_e32 v7, 32, v95
	v_cmp_lt_i32_e32 vcc, v7, v6
	s_waitcnt lgkmcnt(0)
	v_add_f32_e32 v15, v15, v20
	v_cndmask_b32_e32 v6, v95, v7, vcc
	v_lshlrev_b32_e32 v14, 2, v6
	ds_bpermute_b32 v20, v14, v15
	v_lshl_add_u64 v[6:7], s[0:1], 0, v[66:67]
	s_add_i32 s0, s59, s85
	s_ashr_i32 s1, s0, 31
	s_lshl_b64 s[0:1], s[0:1], 11
	s_waitcnt lgkmcnt(0)
	v_add_f32_e32 v15, v15, v20
	v_fmamk_f32 v15, v15, 0x3b800000, v96
	v_cmp_gt_f32_e32 vcc, s79, v15
	v_mul_f32_e32 v20, 0x4b800000, v15
	s_nop 0
	v_cndmask_b32_e32 v15, v15, v20, vcc
	v_rsq_f32_e32 v15, v15
	s_nop 0
	v_mul_f32_e32 v20, 0x45800000, v15
	v_cndmask_b32_e32 v15, v15, v20, vcc
	v_mul_f32_e32 v16, v16, v15
	v_lshlrev_b32_e32 v20, 16, v84
	v_mul_f32_e32 v17, v17, v15
	v_mul_f32_e32 v18, v18, v15
	v_mul_f32_e32 v15, v19, v15
	v_mul_f32_e32 v19, 0xbfb8aa3b, v23
	v_exp_f32_e32 v19, v19
	s_waitcnt vmcnt(0)
; #define LAS __attribute__((address_space(3)))
; __device__ __forceinline__ float bf2f(unsigned u) { return __uint_as_float(u << 16); }
; __device__ __forceinline__ unsigned pk(float lo, float hi) { return pg8::cvt_pk_bf16(lo, hi); }
; __device__ __forceinline__ float dot4(f32x4 v) { return (v[0] * v[0] + v[1] * v[1]) + (v[2] * v[2] + v[3] * v[3]); }
; template <int MODE> __device__ __forceinline__ void gla_item(const Args& a, LAS unsigned char* lds, int cid, int h, GlaPre& pf, int next) {
;     ...
; #pragma unroll
;         for (int i = 0; i < 8; ++i) { const int t = 8 * w + i; const f32x4 v = *(const LAS f32x4*)(OL + t * OLS + 4 * lane);
;             const float rs = rsqrtf(wave_sum(dot4(v)) * (1.f / 256.f) + EPS);
;             const u32x2 rr = rraw[i];
;             float rv[4] = {bf2f(rr.x & 0xffffu), bf2f(rr.x >> 16), bf2f(rr.y & 0xffffu), bf2f(rr.y >> 16)}; float y[4];
; #pragma unroll
;             for (int j = 0; j < 4; ++j) y[j] = v[j] * rs * ng[j] * rv[j] * __builtin_amdgcn_rcpf(1.f + __expf(-rv[j]));
;             u32x2 ov; ov.x = pk(y[0], y[1]); ov.y = pk(y[2], y[3]);
;             *(u32x2*)(OG + (size_t)(row0 + t) * DM + h * 256 + 4 * lane) = ov; }
	v_mul_f32_e32 v16, v2, v16
	v_mul_f32_e32 v16, v16, v20
	v_mul_f32_e32 v20, 0xbfb8aa3b, v20
	v_exp_f32_e32 v20, v20
	v_mul_f32_e32 v17, v3, v17
	v_mul_f32_e32 v17, v17, v21
	v_add_f32_e32 v19, 1.0, v19
	v_add_f32_e32 v20, 1.0, v20
	v_rcp_f32_e32 v20, v20
	v_rcp_f32_e32 v19, v19
	v_mul_f32_e32 v18, v4, v18
	v_mul_f32_e32 v18, v18, v22
	v_mul_f32_e32 v16, v20, v16
	v_mul_f32_e32 v20, 0xbfb8aa3b, v21
	v_exp_f32_e32 v20, v20
	v_mul_f32_e32 v15, v5, v15
	v_mul_f32_e32 v15, v15, v23
	v_mul_f32_e32 v15, v19, v15
	v_add_f32_e32 v20, 1.0, v20
	v_rcp_f32_e32 v20, v20
	s_nop 0
	v_mul_f32_e32 v17, v20, v17
	v_mul_f32_e32 v20, 0xbfb8aa3b, v22
	v_exp_f32_e32 v20, v20
	v_cvt_pk_bf16_f32 v16, v16, v17
	s_nop 0
	v_add_f32_e32 v20, 1.0, v20
	v_rcp_f32_e32 v20, v20
	s_nop 0
	v_mul_f32_e32 v18, v20, v18
	v_cvt_pk_bf16_f32 v17, v18, v15
	v_lshl_add_u64 v[18:19], v[6:7], 0, s[0:1]
	s_mul_i32 s0, s58, 0x410
	v_add_u32_e32 v15, s0, v11
	global_store_dwordx2 v[18:19], v[16:17], off
	ds_read_b128 v[16:19], v15 offset:8192
	s_add_i32 s58, s58, s85
	s_ashr_i32 s59, s58, 31
	s_lshl_b64 s[58:59], s[58:59], 11
	s_add_i32 s1, s0, 0x410
	s_waitcnt lgkmcnt(0)
	v_pk_mul_f32 v[20:21], v[18:19], v[18:19]
	v_pk_mul_f32 v[22:23], v[16:17], v[16:17]
	s_nop 0
	v_pk_mov_b32 v[24:25], v[22:23], v[20:21] op_sel:[1,0]
	v_mov_b32_e32 v23, v21
	v_pk_add_f32 v[20:21], v[24:25], v[22:23]
	v_lshlrev_b32_e32 v22, 16, v83
	v_add_f32_e32 v15, v20, v21
	ds_bpermute_b32 v20, v8, v15
	v_and_b32_e32 v21, 0xffff0000, v82
	v_and_b32_e32 v23, 0xffff0000, v83
	s_waitcnt lgkmcnt(0)
	v_add_f32_e32 v15, v15, v20
	ds_bpermute_b32 v20, v9, v15
	s_waitcnt lgkmcnt(0)
	v_add_f32_e32 v15, v15, v20
	ds_bpermute_b32 v20, v10, v15
	s_waitcnt lgkmcnt(0)
	v_add_f32_e32 v15, v15, v20
	ds_bpermute_b32 v20, v12, v15
	s_waitcnt lgkmcnt(0)
	v_add_f32_e32 v15, v15, v20
	ds_bpermute_b32 v20, v13, v15
	s_waitcnt lgkmcnt(0)
	v_add_f32_e32 v15, v15, v20
	ds_bpermute_b32 v20, v14, v15
	s_waitcnt lgkmcnt(0)
	v_add_f32_e32 v15, v15, v20
	v_fmamk_f32 v15, v15, 0x3b800000, v96
	v_cmp_gt_f32_e32 vcc, s79, v15
	v_mul_f32_e32 v20, 0x4b800000, v15
	s_nop 0
	v_cndmask_b32_e32 v15, v15, v20, vcc
	v_rsq_f32_e32 v15, v15
	s_nop 0
	v_mul_f32_e32 v20, 0x45800000, v15
	v_cndmask_b32_e32 v15, v15, v20, vcc
	v_mul_f32_e32 v16, v16, v15
	v_lshlrev_b32_e32 v20, 16, v82
	v_mul_f32_e32 v16, v2, v16
	v_mul_f32_e32 v16, v16, v20
	v_mul_f32_e32 v20, 0xbfb8aa3b, v20
	v_exp_f32_e32 v20, v20
	v_mul_f32_e32 v17, v17, v15
	v_mul_f32_e32 v17, v3, v17
	v_mul_f32_e32 v17, v17, v21
	v_add_f32_e32 v20, 1.0, v20
	v_rcp_f32_e32 v20, v20
	v_mul_f32_e32 v18, v18, v15
	v_mul_f32_e32 v15, v19, v15
	v_mul_f32_e32 v19, 0xbfb8aa3b, v23
	v_mul_f32_e32 v16, v20, v16
	v_mul_f32_e32 v20, 0xbfb8aa3b, v21
	v_exp_f32_e32 v20, v20
	v_exp_f32_e32 v19, v19
	v_mul_f32_e32 v18, v4, v18
	v_mul_f32_e32 v15, v5, v15
	v_add_f32_e32 v20, 1.0, v20
	v_rcp_f32_e32 v20, v20
	v_add_f32_e32 v19, 1.0, v19
	v_rcp_f32_e32 v19, v19
	v_mul_f32_e32 v18, v18, v22
	v_mul_f32_e32 v17, v20, v17
	v_mul_f32_e32 v20, 0xbfb8aa3b, v22
	v_exp_f32_e32 v20, v20
	v_mul_f32_e32 v15, v15, v23
	v_mul_f32_e32 v15, v19, v15
	v_cvt_pk_bf16_f32 v16, v16, v17
	v_add_f32_e32 v20, 1.0, v20
	v_rcp_f32_e32 v20, v20
	s_nop 0
	v_mul_f32_e32 v18, v20, v18
	v_cvt_pk_bf16_f32 v17, v18, v15
	v_lshl_add_u64 v[18:19], v[6:7], 0, s[58:59]
	v_add_u32_e32 v15, s1, v11
	global_store_dwordx2 v[18:19], v[16:17], off
	ds_read_b128 v[16:19], v15 offset:8192
	s_add_i32 s58, s57, s85
	s_ashr_i32 s59, s58, 31
	s_lshl_b64 s[58:59], s[58:59], 11
	s_add_i32 s1, s0, 0x820
	s_waitcnt lgkmcnt(0)
	v_pk_mul_f32 v[20:21], v[18:19], v[18:19]
	v_pk_mul_f32 v[22:23], v[16:17], v[16:17]
	s_ashr_i32 s57, s56, 31
	v_pk_mov_b32 v[24:25], v[22:23], v[20:21] op_sel:[1,0]
	v_mov_b32_e32 v23, v21
	v_pk_add_f32 v[20:21], v[24:25], v[22:23]
	v_lshlrev_b32_e32 v22, 16, v81
	v_add_f32_e32 v15, v20, v21
	ds_bpermute_b32 v20, v8, v15
	v_and_b32_e32 v21, 0xffff0000, v80
	v_and_b32_e32 v23, 0xffff0000, v81
	s_lshl_b64 s[56:57], s[56:57], 11
	s_waitcnt lgkmcnt(0)
	v_add_f32_e32 v15, v15, v20
	ds_bpermute_b32 v20, v9, v15
	s_waitcnt lgkmcnt(0)
	v_add_f32_e32 v15, v15, v20
	ds_bpermute_b32 v20, v10, v15
	s_waitcnt lgkmcnt(0)
	v_add_f32_e32 v15, v15, v20
	ds_bpermute_b32 v20, v12, v15
	s_waitcnt lgkmcnt(0)
	v_add_f32_e32 v15, v15, v20
	ds_bpermute_b32 v20, v13, v15
	s_waitcnt lgkmcnt(0)
	v_add_f32_e32 v15, v15, v20
	ds_bpermute_b32 v20, v14, v15
	s_waitcnt lgkmcnt(0)
	v_add_f32_e32 v15, v15, v20
	v_fmamk_f32 v15, v15, 0x3b800000, v96
	v_cmp_gt_f32_e32 vcc, s79, v15
	v_mul_f32_e32 v20, 0x4b800000, v15
	s_nop 0
	v_cndmask_b32_e32 v15, v15, v20, vcc
	v_rsq_f32_e32 v15, v15
	s_nop 0
	v_mul_f32_e32 v20, 0x45800000, v15
	v_cndmask_b32_e32 v15, v15, v20, vcc
	v_mul_f32_e32 v16, v16, v15
	v_lshlrev_b32_e32 v20, 16, v80
	v_mul_f32_e32 v16, v2, v16
	v_mul_f32_e32 v16, v16, v20
	v_mul_f32_e32 v20, 0xbfb8aa3b, v20
	v_exp_f32_e32 v20, v20
	v_mul_f32_e32 v17, v17, v15
	v_mul_f32_e32 v17, v3, v17
	v_mul_f32_e32 v17, v17, v21
	v_add_f32_e32 v20, 1.0, v20
	v_rcp_f32_e32 v20, v20
	v_mul_f32_e32 v18, v18, v15
	v_mul_f32_e32 v15, v19, v15
	v_mul_f32_e32 v19, 0xbfb8aa3b, v23
	v_mul_f32_e32 v16, v20, v16
	v_mul_f32_e32 v20, 0xbfb8aa3b, v21
	v_exp_f32_e32 v20, v20
	v_exp_f32_e32 v19, v19
	v_mul_f32_e32 v18, v4, v18
	v_mul_f32_e32 v15, v5, v15
	v_add_f32_e32 v20, 1.0, v20
	v_rcp_f32_e32 v20, v20
	v_add_f32_e32 v19, 1.0, v19
	v_rcp_f32_e32 v19, v19
	v_mul_f32_e32 v18, v18, v22
	v_mul_f32_e32 v17, v20, v17
	v_mul_f32_e32 v20, 0xbfb8aa3b, v22
	v_exp_f32_e32 v20, v20
	v_mul_f32_e32 v15, v15, v23
	v_mul_f32_e32 v15, v19, v15
	v_cvt_pk_bf16_f32 v16, v16, v17
	v_add_f32_e32 v20, 1.0, v20
	v_rcp_f32_e32 v20, v20
	s_nop 0
	v_mul_f32_e32 v18, v20, v18
	v_cvt_pk_bf16_f32 v17, v18, v15
	v_lshl_add_u64 v[18:19], v[6:7], 0, s[58:59]
	v_add_u32_e32 v15, s1, v11
	global_store_dwordx2 v[18:19], v[16:17], off
	ds_read_b128 v[16:19], v15 offset:8192
	s_add_i32 s1, s0, 0xc30
	s_waitcnt lgkmcnt(0)
; #define LAS __attribute__((address_space(3)))
; __device__ __forceinline__ float bf2f(unsigned u) { return __uint_as_float(u << 16); }
; __device__ __forceinline__ unsigned pk(float lo, float hi) { return pg8::cvt_pk_bf16(lo, hi); }
; __device__ __forceinline__ float dot4(f32x4 v) { return (v[0] * v[0] + v[1] * v[1]) + (v[2] * v[2] + v[3] * v[3]); }
; template <int MODE> __device__ __forceinline__ void gla_item(const Args& a, LAS unsigned char* lds, int cid, int h, GlaPre& pf, int next) {
;     ...
; #pragma unroll
;         for (int i = 0; i < 8; ++i) { const int t = 8 * w + i; const f32x4 v = *(const LAS f32x4*)(OL + t * OLS + 4 * lane);
;             const float rs = rsqrtf(wave_sum(dot4(v)) * (1.f / 256.f) + EPS);
;             const u32x2 rr = rraw[i];
;             float rv[4] = {bf2f(rr.x & 0xffffu), bf2f(rr.x >> 16), bf2f(rr.y & 0xffffu), bf2f(rr.y >> 16)}; float y[4];
; #pragma unroll
;             for (int j = 0; j < 4; ++j) y[j] = v[j] * rs * ng[j] * rv[j] * __builtin_amdgcn_rcpf(1.f + __expf(-rv[j]));
;             u32x2 ov; ov.x = pk(y[0], y[1]); ov.y = pk(y[2], y[3]);
;             *(u32x2*)(OG + (size_t)(row0 + t) * DM + h * 256 + 4 * lane) = ov; }
	v_pk_mul_f32 v[20:21], v[18:19], v[18:19]
	v_pk_mul_f32 v[22:23], v[16:17], v[16:17]
	s_nop 0
	v_pk_mov_b32 v[24:25], v[22:23], v[20:21] op_sel:[1,0]
	v_mov_b32_e32 v23, v21
	v_pk_add_f32 v[20:21], v[24:25], v[22:23]
	v_lshlrev_b32_e32 v22, 16, v79
	v_add_f32_e32 v15, v20, v21
	ds_bpermute_b32 v20, v8, v15
	v_and_b32_e32 v21, 0xffff0000, v78
	v_and_b32_e32 v23, 0xffff0000, v79
	s_waitcnt lgkmcnt(0)
	v_add_f32_e32 v15, v15, v20
	ds_bpermute_b32 v20, v9, v15
	s_waitcnt lgkmcnt(0)
	v_add_f32_e32 v15, v15, v20
	ds_bpermute_b32 v20, v10, v15
	s_waitcnt lgkmcnt(0)
	v_add_f32_e32 v15, v15, v20
	ds_bpermute_b32 v20, v12, v15
	s_waitcnt lgkmcnt(0)
	v_add_f32_e32 v15, v15, v20
	ds_bpermute_b32 v20, v13, v15
	s_waitcnt lgkmcnt(0)
	v_add_f32_e32 v15, v15, v20
	ds_bpermute_b32 v20, v14, v15
	s_waitcnt lgkmcnt(0)
	v_add_f32_e32 v15, v15, v20
	v_fmamk_f32 v15, v15, 0x3b800000, v96
	v_cmp_gt_f32_e32 vcc, s79, v15
	v_mul_f32_e32 v20, 0x4b800000, v15
	s_nop 0
	v_cndmask_b32_e32 v15, v15, v20, vcc
	v_rsq_f32_e32 v15, v15
	s_nop 0
	v_mul_f32_e32 v20, 0x45800000, v15
	v_cndmask_b32_e32 v15, v15, v20, vcc
	v_mul_f32_e32 v16, v16, v15
	v_lshlrev_b32_e32 v20, 16, v78
	v_mul_f32_e32 v16, v2, v16
	v_mul_f32_e32 v16, v16, v20
	v_mul_f32_e32 v20, 0xbfb8aa3b, v20
	v_exp_f32_e32 v20, v20
	v_mul_f32_e32 v17, v17, v15
	v_mul_f32_e32 v17, v3, v17
	v_mul_f32_e32 v17, v17, v21
	v_add_f32_e32 v20, 1.0, v20
	v_rcp_f32_e32 v20, v20
	v_mul_f32_e32 v18, v18, v15
	v_mul_f32_e32 v15, v19, v15
	v_mul_f32_e32 v19, 0xbfb8aa3b, v23
	v_mul_f32_e32 v16, v20, v16
	v_mul_f32_e32 v20, 0xbfb8aa3b, v21
	v_exp_f32_e32 v20, v20
	v_exp_f32_e32 v19, v19
	v_mul_f32_e32 v18, v4, v18
	v_mul_f32_e32 v15, v5, v15
	v_add_f32_e32 v20, 1.0, v20
	v_rcp_f32_e32 v20, v20
	v_add_f32_e32 v19, 1.0, v19
	v_rcp_f32_e32 v19, v19
	v_mul_f32_e32 v18, v18, v22
	v_mul_f32_e32 v17, v20, v17
	v_mul_f32_e32 v20, 0xbfb8aa3b, v22
	v_exp_f32_e32 v20, v20
	v_mul_f32_e32 v15, v15, v23
	v_mul_f32_e32 v15, v19, v15
	v_cvt_pk_bf16_f32 v16, v16, v17
	v_add_f32_e32 v20, 1.0, v20
	v_rcp_f32_e32 v20, v20
	s_nop 0
	v_mul_f32_e32 v18, v20, v18
	v_cvt_pk_bf16_f32 v17, v18, v15
	v_lshl_add_u64 v[18:19], v[6:7], 0, s[56:57]
	v_add_u32_e32 v15, s1, v11
	global_store_dwordx2 v[18:19], v[16:17], off
	ds_read_b128 v[16:19], v15 offset:8192
	s_add_i32 s56, s55, s85
	s_ashr_i32 s57, s56, 31
	s_lshl_b64 s[56:57], s[56:57], 11
	s_add_i32 s1, s0, 0x1040
	s_waitcnt lgkmcnt(0)
	v_pk_mul_f32 v[20:21], v[18:19], v[18:19]
	v_pk_mul_f32 v[22:23], v[16:17], v[16:17]
	s_ashr_i32 s55, s54, 31
	v_pk_mov_b32 v[24:25], v[22:23], v[20:21] op_sel:[1,0]
	v_mov_b32_e32 v23, v21
	v_pk_add_f32 v[20:21], v[24:25], v[22:23]
	v_lshlrev_b32_e32 v22, 16, v61
	v_add_f32_e32 v15, v20, v21
	ds_bpermute_b32 v20, v8, v15
	v_and_b32_e32 v21, 0xffff0000, v60
	v_and_b32_e32 v23, 0xffff0000, v61
	s_lshl_b64 s[54:55], s[54:55], 11
	s_waitcnt lgkmcnt(0)
	v_add_f32_e32 v15, v15, v20
	ds_bpermute_b32 v20, v9, v15
	s_waitcnt lgkmcnt(0)
	v_add_f32_e32 v15, v15, v20
	ds_bpermute_b32 v20, v10, v15
	s_waitcnt lgkmcnt(0)
	v_add_f32_e32 v15, v15, v20
	ds_bpermute_b32 v20, v12, v15
	s_waitcnt lgkmcnt(0)
	v_add_f32_e32 v15, v15, v20
	ds_bpermute_b32 v20, v13, v15
	s_waitcnt lgkmcnt(0)
	v_add_f32_e32 v15, v15, v20
	ds_bpermute_b32 v20, v14, v15
	s_waitcnt lgkmcnt(0)
	v_add_f32_e32 v15, v15, v20
	v_fmamk_f32 v15, v15, 0x3b800000, v96
	v_cmp_gt_f32_e32 vcc, s79, v15
	v_mul_f32_e32 v20, 0x4b800000, v15
	s_nop 0
	v_cndmask_b32_e32 v15, v15, v20, vcc
	v_rsq_f32_e32 v15, v15
	s_nop 0
	v_mul_f32_e32 v20, 0x45800000, v15
	v_cndmask_b32_e32 v15, v15, v20, vcc
	v_mul_f32_e32 v16, v16, v15
	v_lshlrev_b32_e32 v20, 16, v60
	v_mul_f32_e32 v16, v2, v16
	v_mul_f32_e32 v16, v16, v20
	v_mul_f32_e32 v20, 0xbfb8aa3b, v20
	v_exp_f32_e32 v20, v20
	v_mul_f32_e32 v17, v17, v15
	v_mul_f32_e32 v17, v3, v17
	v_mul_f32_e32 v17, v17, v21
	v_add_f32_e32 v20, 1.0, v20
	v_rcp_f32_e32 v20, v20
	v_mul_f32_e32 v18, v18, v15
	v_mul_f32_e32 v15, v19, v15
	v_mul_f32_e32 v19, 0xbfb8aa3b, v23
	v_mul_f32_e32 v16, v20, v16
	v_mul_f32_e32 v20, 0xbfb8aa3b, v21
	v_exp_f32_e32 v20, v20
	v_exp_f32_e32 v19, v19
	v_mul_f32_e32 v18, v4, v18
	v_mul_f32_e32 v15, v5, v15
	v_add_f32_e32 v20, 1.0, v20
	v_rcp_f32_e32 v20, v20
	v_add_f32_e32 v19, 1.0, v19
	v_rcp_f32_e32 v19, v19
	v_mul_f32_e32 v18, v18, v22
	v_mul_f32_e32 v17, v20, v17
	v_mul_f32_e32 v20, 0xbfb8aa3b, v22
	v_exp_f32_e32 v20, v20
	v_mul_f32_e32 v15, v15, v23
	v_mul_f32_e32 v15, v19, v15
	v_cvt_pk_bf16_f32 v16, v16, v17
	v_add_f32_e32 v20, 1.0, v20
	v_rcp_f32_e32 v20, v20
	s_nop 0
	v_mul_f32_e32 v18, v20, v18
	v_cvt_pk_bf16_f32 v17, v18, v15
	v_lshl_add_u64 v[18:19], v[6:7], 0, s[56:57]
	v_add_u32_e32 v15, s1, v11
	global_store_dwordx2 v[18:19], v[16:17], off
	ds_read_b128 v[16:19], v15 offset:8192
	s_add_i32 s1, s0, 0x1450
	s_addk_i32 s0, 0x1860
	s_waitcnt lgkmcnt(0)
	v_pk_mul_f32 v[20:21], v[18:19], v[18:19]
	v_pk_mul_f32 v[22:23], v[16:17], v[16:17]
	s_nop 0
	v_pk_mov_b32 v[24:25], v[22:23], v[20:21] op_sel:[1,0]
	v_mov_b32_e32 v23, v21
	v_pk_add_f32 v[20:21], v[24:25], v[22:23]
	v_lshlrev_b32_e32 v22, 16, v59
	v_add_f32_e32 v15, v20, v21
	ds_bpermute_b32 v20, v8, v15
	v_and_b32_e32 v21, 0xffff0000, v58
	v_and_b32_e32 v23, 0xffff0000, v59
	s_waitcnt lgkmcnt(0)
	v_add_f32_e32 v15, v15, v20
	ds_bpermute_b32 v20, v9, v15
	s_waitcnt lgkmcnt(0)
	v_add_f32_e32 v15, v15, v20
	ds_bpermute_b32 v20, v10, v15
	s_waitcnt lgkmcnt(0)
	v_add_f32_e32 v15, v15, v20
	ds_bpermute_b32 v20, v12, v15
	s_waitcnt lgkmcnt(0)
	v_add_f32_e32 v15, v15, v20
	ds_bpermute_b32 v20, v13, v15
	s_waitcnt lgkmcnt(0)
	v_add_f32_e32 v15, v15, v20
	ds_bpermute_b32 v20, v14, v15
	s_waitcnt lgkmcnt(0)
; #define LAS __attribute__((address_space(3)))
; __device__ __forceinline__ float bf2f(unsigned u) { return __uint_as_float(u << 16); }
; __device__ __forceinline__ unsigned pk(float lo, float hi) { return pg8::cvt_pk_bf16(lo, hi); }
; __device__ __forceinline__ float dot4(f32x4 v) { return (v[0] * v[0] + v[1] * v[1]) + (v[2] * v[2] + v[3] * v[3]); }
; template <int MODE> __device__ __forceinline__ void gla_item(const Args& a, LAS unsigned char* lds, int cid, int h, GlaPre& pf, int next) {
;     ...
; #pragma unroll
;         for (int i = 0; i < 8; ++i) { const int t = 8 * w + i; const f32x4 v = *(const LAS f32x4*)(OL + t * OLS + 4 * lane);
;             const float rs = rsqrtf(wave_sum(dot4(v)) * (1.f / 256.f) + EPS);
;             const u32x2 rr = rraw[i];
;             float rv[4] = {bf2f(rr.x & 0xffffu), bf2f(rr.x >> 16), bf2f(rr.y & 0xffffu), bf2f(rr.y >> 16)}; float y[4];
; #pragma unroll
;             for (int j = 0; j < 4; ++j) y[j] = v[j] * rs * ng[j] * rv[j] * __builtin_amdgcn_rcpf(1.f + __expf(-rv[j]));
;             u32x2 ov; ov.x = pk(y[0], y[1]); ov.y = pk(y[2], y[3]);
;             *(u32x2*)(OG + (size_t)(row0 + t) * DM + h * 256 + 4 * lane) = ov; }
;     }
;     __syncthreads();
	v_add_f32_e32 v15, v15, v20
	v_fmamk_f32 v15, v15, 0x3b800000, v96
	v_cmp_gt_f32_e32 vcc, s79, v15
	v_mul_f32_e32 v20, 0x4b800000, v15
	s_nop 0
	v_cndmask_b32_e32 v15, v15, v20, vcc
	v_rsq_f32_e32 v15, v15
	s_nop 0
	v_mul_f32_e32 v20, 0x45800000, v15
	v_cndmask_b32_e32 v15, v15, v20, vcc
	v_mul_f32_e32 v16, v16, v15
	v_lshlrev_b32_e32 v20, 16, v58
	v_mul_f32_e32 v16, v2, v16
	v_mul_f32_e32 v16, v16, v20
	v_mul_f32_e32 v20, 0xbfb8aa3b, v20
	v_exp_f32_e32 v20, v20
	v_mul_f32_e32 v17, v17, v15
	v_mul_f32_e32 v17, v3, v17
	v_mul_f32_e32 v17, v17, v21
	v_add_f32_e32 v20, 1.0, v20
	v_rcp_f32_e32 v20, v20
	v_mul_f32_e32 v18, v18, v15
	v_mul_f32_e32 v15, v19, v15
	v_mul_f32_e32 v19, 0xbfb8aa3b, v23
	v_mul_f32_e32 v16, v20, v16
	v_mul_f32_e32 v20, 0xbfb8aa3b, v21
	v_exp_f32_e32 v20, v20
	v_exp_f32_e32 v19, v19
	v_mul_f32_e32 v18, v4, v18
	v_mul_f32_e32 v15, v5, v15
	v_add_f32_e32 v20, 1.0, v20
	v_rcp_f32_e32 v20, v20
	v_add_f32_e32 v19, 1.0, v19
	v_rcp_f32_e32 v19, v19
	v_mul_f32_e32 v18, v18, v22
	v_mul_f32_e32 v17, v20, v17
	v_mul_f32_e32 v20, 0xbfb8aa3b, v22
	v_exp_f32_e32 v20, v20
	v_mul_f32_e32 v15, v15, v23
	v_mul_f32_e32 v15, v19, v15
	v_cvt_pk_bf16_f32 v16, v16, v17
	v_add_f32_e32 v20, 1.0, v20
	v_rcp_f32_e32 v20, v20
	s_nop 0
	v_mul_f32_e32 v18, v20, v18
	v_cvt_pk_bf16_f32 v17, v18, v15
	v_lshl_add_u64 v[18:19], v[6:7], 0, s[54:55]
	v_add_u32_e32 v15, s1, v11
	global_store_dwordx2 v[18:19], v[16:17], off
	ds_read_b128 v[16:19], v15 offset:8192
	s_add_i32 s54, s53, s85
	s_ashr_i32 s55, s54, 31
	s_lshl_b64 s[54:55], s[54:55], 11
	v_add_u32_e32 v11, s0, v11
	s_waitcnt lgkmcnt(0)
	v_pk_mul_f32 v[20:21], v[18:19], v[18:19]
	v_pk_mul_f32 v[22:23], v[16:17], v[16:17]
	s_add_i32 s0, s52, s85
	v_pk_mov_b32 v[24:25], v[22:23], v[20:21] op_sel:[1,0]
	v_mov_b32_e32 v23, v21
	v_pk_add_f32 v[20:21], v[24:25], v[22:23]
	v_lshlrev_b32_e32 v22, 16, v57
	v_add_f32_e32 v15, v20, v21
	ds_bpermute_b32 v20, v8, v15
	v_and_b32_e32 v21, 0xffff0000, v56
	v_and_b32_e32 v23, 0xffff0000, v57
	s_ashr_i32 s1, s0, 31
	s_lshl_b64 s[0:1], s[0:1], 11
	s_waitcnt lgkmcnt(0)
	v_add_f32_e32 v15, v15, v20
	ds_bpermute_b32 v20, v9, v15
	s_add_u32 s10, s10, s42
	s_addc_u32 s11, s11, s43
	s_waitcnt lgkmcnt(0)
	v_add_f32_e32 v15, v15, v20
	ds_bpermute_b32 v20, v10, v15
	s_waitcnt lgkmcnt(0)
	v_add_f32_e32 v15, v15, v20
	ds_bpermute_b32 v20, v12, v15
	s_waitcnt lgkmcnt(0)
	v_add_f32_e32 v15, v15, v20
	ds_bpermute_b32 v20, v13, v15
	s_waitcnt lgkmcnt(0)
	v_add_f32_e32 v15, v15, v20
	ds_bpermute_b32 v20, v14, v15
	s_waitcnt lgkmcnt(0)
	v_add_f32_e32 v15, v15, v20
	v_fmamk_f32 v15, v15, 0x3b800000, v96
	v_cmp_gt_f32_e32 vcc, s79, v15
	v_mul_f32_e32 v20, 0x4b800000, v15
	s_nop 0
	v_cndmask_b32_e32 v15, v15, v20, vcc
	v_rsq_f32_e32 v15, v15
	s_nop 0
	v_mul_f32_e32 v20, 0x45800000, v15
	v_cndmask_b32_e32 v15, v15, v20, vcc
	v_mul_f32_e32 v16, v16, v15
	v_lshlrev_b32_e32 v20, 16, v56
	v_mul_f32_e32 v16, v2, v16
	v_mul_f32_e32 v16, v16, v20
	v_mul_f32_e32 v20, 0xbfb8aa3b, v20
	v_exp_f32_e32 v20, v20
	v_mul_f32_e32 v17, v17, v15
	v_mul_f32_e32 v17, v3, v17
	v_mul_f32_e32 v17, v17, v21
	v_add_f32_e32 v20, 1.0, v20
	v_rcp_f32_e32 v20, v20
	v_mul_f32_e32 v18, v18, v15
	v_mul_f32_e32 v15, v19, v15
	v_mul_f32_e32 v19, 0xbfb8aa3b, v23
	v_mul_f32_e32 v16, v20, v16
	v_mul_f32_e32 v20, 0xbfb8aa3b, v21
	v_exp_f32_e32 v20, v20
	v_exp_f32_e32 v19, v19
	v_mul_f32_e32 v18, v4, v18
	v_mul_f32_e32 v18, v18, v22
	v_add_f32_e32 v20, 1.0, v20
	v_rcp_f32_e32 v20, v20
	v_add_f32_e32 v19, 1.0, v19
	v_rcp_f32_e32 v19, v19
	v_mul_f32_e32 v15, v5, v15
	v_mul_f32_e32 v17, v20, v17
	v_mul_f32_e32 v20, 0xbfb8aa3b, v22
	v_exp_f32_e32 v20, v20
	v_mul_f32_e32 v15, v15, v23
	v_mul_f32_e32 v15, v19, v15
	v_cvt_pk_bf16_f32 v16, v16, v17
	v_add_f32_e32 v20, 1.0, v20
	v_rcp_f32_e32 v20, v20
	s_nop 0
	v_mul_f32_e32 v18, v20, v18
	v_cvt_pk_bf16_f32 v17, v18, v15
	v_lshl_add_u64 v[18:19], v[6:7], 0, s[54:55]
	global_store_dwordx2 v[18:19], v[16:17], off
	ds_read_b128 v[16:19], v11 offset:8192
	s_waitcnt lgkmcnt(0)
	v_pk_mul_f32 v[20:21], v[18:19], v[18:19]
	v_pk_mul_f32 v[22:23], v[16:17], v[16:17]
	s_nop 0
	v_pk_mov_b32 v[24:25], v[22:23], v[20:21] op_sel:[1,0]
	v_mov_b32_e32 v23, v21
	v_pk_add_f32 v[20:21], v[24:25], v[22:23]
	s_nop 0
	v_add_f32_e32 v11, v20, v21
	ds_bpermute_b32 v8, v8, v11
	s_waitcnt lgkmcnt(0)
	v_add_f32_e32 v8, v11, v8
	ds_bpermute_b32 v9, v9, v8
	v_lshlrev_b32_e32 v11, 16, v55
	s_waitcnt lgkmcnt(0)
	v_add_f32_e32 v8, v8, v9
	ds_bpermute_b32 v9, v10, v8
	v_and_b32_e32 v10, 0xffff0000, v54
	s_waitcnt lgkmcnt(0)
	v_add_f32_e32 v8, v8, v9
	ds_bpermute_b32 v9, v12, v8
	v_and_b32_e32 v12, 0xffff0000, v55
	s_waitcnt lgkmcnt(0)
	v_add_f32_e32 v8, v8, v9
	ds_bpermute_b32 v9, v13, v8
	s_waitcnt lgkmcnt(0)
	v_add_f32_e32 v8, v8, v9
	ds_bpermute_b32 v9, v14, v8
	s_waitcnt lgkmcnt(0)
	v_add_f32_e32 v8, v8, v9
	v_fmamk_f32 v8, v8, 0x3b800000, v96
	v_cmp_gt_f32_e32 vcc, s79, v8
	v_mul_f32_e32 v9, 0x4b800000, v8
	s_nop 0
	v_cndmask_b32_e32 v8, v8, v9, vcc
	v_rsq_f32_e32 v8, v8
	s_nop 0
	v_mul_f32_e32 v9, 0x45800000, v8
	v_cndmask_b32_e32 v8, v8, v9, vcc
	v_mul_f32_e32 v13, v16, v8
	v_lshlrev_b32_e32 v9, 16, v54
	v_mul_f32_e32 v2, v2, v13
	v_mul_f32_e32 v2, v2, v9
	v_mul_f32_e32 v9, 0xbfb8aa3b, v9
	v_exp_f32_e32 v9, v9
	s_andn2_b64 vcc, exec, s[66:67]
	v_add_f32_e32 v9, 1.0, v9
	v_rcp_f32_e32 v9, v9
	s_nop 0
	v_mul_f32_e32 v2, v9, v2
	v_mul_f32_e32 v9, v17, v8
	v_mul_f32_e32 v3, v3, v9
	v_mul_f32_e32 v9, 0xbfb8aa3b, v10
	v_exp_f32_e32 v9, v9
	v_mul_f32_e32 v3, v3, v10
	v_add_f32_e32 v9, 1.0, v9
	v_rcp_f32_e32 v9, v9
	s_nop 0
	v_mul_f32_e32 v3, v9, v3
	v_mul_f32_e32 v9, v18, v8
	v_mul_f32_e32 v8, v19, v8
	v_mul_f32_e32 v4, v4, v9
	v_mul_f32_e32 v9, 0xbfb8aa3b, v11
	v_mul_f32_e32 v5, v5, v8
	v_mul_f32_e32 v8, 0xbfb8aa3b, v12
	v_exp_f32_e32 v9, v9
	v_exp_f32_e32 v8, v8
	v_mul_f32_e32 v4, v4, v11
	v_mul_f32_e32 v5, v5, v12
	v_add_f32_e32 v9, 1.0, v9
	v_add_f32_e32 v8, 1.0, v8
	v_rcp_f32_e32 v9, v9
	v_rcp_f32_e32 v8, v8
	v_cvt_pk_bf16_f32 v2, v2, v3
	v_mul_f32_e32 v4, v9, v4
	v_mul_f32_e32 v5, v8, v5
	v_cvt_pk_bf16_f32 v3, v4, v5
	v_lshl_add_u64 v[4:5], v[6:7], 0, s[0:1]
	global_store_dwordx2 v[4:5], v[2:3], off
	s_barrier
	s_cbranch_vccz .LBB0_720

; __device__ __forceinline__ float bf2f(unsigned u) { return __uint_as_float(u << 16); }
; __device__ __forceinline__ unsigned f2bf(float f) { unsigned u = __float_as_uint(f); return (u + 0x7fffu + ((u >> 16) & 1u)) >> 16; }
; template <int MODE> __device__ __forceinline__ void gla_item(const Args& a, LAS unsigned char* lds, int cid, int h, GlaPre& pf, int next) {
;     ...
; #pragma unroll
;         for (int i = 0; i < 16; ++i) { const float b = bc[i] + off; const int t = 16 * tg + i;
;             const float qe = bf2f(qraw[i]) * __expf(b) * 0.08838834764831845f, ke = bf2f(kraw[i]) * __expf(-b);
;             QE[t * QES + dk] = (bf16_t)f2bf(qe); KE[t * QES + dk] = (bf16_t)f2bf(ke); }
;     }
.LBB0_716:
	s_or_b64 exec, exec, s[0:1]
	v_add_f32_e32 v5, v5, v124
	v_and_b32_e32 v123, 63, v6
	v_mul_f32_e32 v6, 0x3fb8aa3b, v5
	v_exp_f32_e32 v6, v6
	v_mul_f32_e32 v5, 0xbfb8aa3b, v5
	v_exp_f32_e32 v5, v5
	v_lshlrev_b32_e32 v83, 16, v83
	v_mul_f32_e32 v6, v6, v83
	s_movk_i32 s0, 0x880
	v_mul_f32_e32 v6, 0x3db504f3, v6
	v_lshlrev_b32_e32 v82, 16, v82
	v_mul_lo_u32 v29, v29, s0
	v_mul_f32_e32 v5, v5, v82
	v_bfe_u32 v82, v6, 16, 1
	v_or_b32_e32 v29, v29, v2
	v_add3_u32 v6, v6, v82, s82
	v_lshl_add_u32 v29, v29, 1, 0
	ds_write_b16_d16_hi v29, v6 offset:8192
	v_bfe_u32 v6, v5, 16, 1
	v_add3_u32 v5, v5, v6, s82
	ds_write_b16_d16_hi v29, v5 offset:25600
	v_add_f32_e32 v5, v66, v124
	v_mul_f32_e32 v6, 0x3fb8aa3b, v5
	v_exp_f32_e32 v6, v6
	v_mul_f32_e32 v5, 0xbfb8aa3b, v5
	v_exp_f32_e32 v5, v5
	v_lshlrev_b32_e32 v29, 16, v81
	v_mul_f32_e32 v6, v6, v29
	v_mul_f32_e32 v6, 0x3db504f3, v6
	v_lshlrev_b32_e32 v29, 16, v80
	v_mul_f32_e32 v29, v5, v29
	v_bfe_u32 v5, v6, 16, 1
	v_add3_u32 v6, v6, v5, s82
	v_mad_u64_u32 v[4:5], s[0:1], v4, s83, v[2:3]
	v_lshl_add_u32 v2, v4, 1, 0
	v_bfe_u32 v4, v29, 16, 1
	v_add3_u32 v4, v29, v4, s82
	ds_write_b16_d16_hi v2, v4 offset:25600
	v_add_f32_e32 v4, v139, v124
	v_mul_f32_e32 v5, 0x3fb8aa3b, v4
	v_exp_f32_e32 v5, v5
	v_mul_f32_e32 v4, 0xbfb8aa3b, v4
	v_exp_f32_e32 v4, v4
	ds_write_b16_d16_hi v2, v6 offset:8192
	v_lshlrev_b32_e32 v6, 16, v79
	v_mul_f32_e32 v5, v5, v6
	v_mul_f32_e32 v5, 0x3db504f3, v5
	v_lshlrev_b32_e32 v6, 16, v78
	v_mul_f32_e32 v4, v4, v6
	v_bfe_u32 v6, v5, 16, 1
	v_add3_u32 v5, v5, v6, s82
	ds_write_b16_d16_hi v2, v5 offset:8464
	v_bfe_u32 v5, v4, 16, 1
	v_add3_u32 v4, v4, v5, s82
	ds_write_b16_d16_hi v2, v4 offset:25872
	v_add_f32_e32 v4, v140, v124
	v_mul_f32_e32 v5, 0x3fb8aa3b, v4
	v_exp_f32_e32 v5, v5
	v_mul_f32_e32 v4, 0xbfb8aa3b, v4
	v_exp_f32_e32 v4, v4
	v_lshlrev_b32_e32 v6, 16, v77
	v_mul_f32_e32 v5, v5, v6
	v_mul_f32_e32 v5, 0x3db504f3, v5
	v_lshlrev_b32_e32 v6, 16, v73
	v_mul_f32_e32 v4, v4, v6
	v_bfe_u32 v6, v5, 16, 1
	v_add3_u32 v5, v5, v6, s82
	ds_write_b16_d16_hi v2, v5 offset:8736
	v_bfe_u32 v5, v4, 16, 1
	v_add3_u32 v4, v4, v5, s82
	ds_write_b16_d16_hi v2, v4 offset:26144
	v_add_f32_e32 v4, v141, v124
	v_mul_f32_e32 v5, 0x3fb8aa3b, v4
	v_exp_f32_e32 v5, v5
	v_mul_f32_e32 v4, 0xbfb8aa3b, v4
	v_exp_f32_e32 v4, v4
	v_lshlrev_b32_e32 v6, 16, v75
	v_mul_f32_e32 v5, v5, v6
	v_mul_f32_e32 v5, 0x3db504f3, v5
	v_lshlrev_b32_e32 v6, 16, v33
	v_mul_f32_e32 v4, v4, v6
	v_bfe_u32 v6, v5, 16, 1
	v_add3_u32 v5, v5, v6, s82
	ds_write_b16_d16_hi v2, v5 offset:9008
	v_bfe_u32 v5, v4, 16, 1
	v_add3_u32 v4, v4, v5, s82
	ds_write_b16_d16_hi v2, v4 offset:26416
	v_add_f32_e32 v4, v142, v124
	v_mul_f32_e32 v5, 0x3fb8aa3b, v4
	v_exp_f32_e32 v5, v5
	v_mul_f32_e32 v4, 0xbfb8aa3b, v4
	v_exp_f32_e32 v4, v4
	v_lshlrev_b32_e32 v6, 16, v32
	v_mul_f32_e32 v5, v5, v6
	v_mul_f32_e32 v5, 0x3db504f3, v5
	v_lshlrev_b32_e32 v6, 16, v31
	v_mul_f32_e32 v4, v4, v6
	v_bfe_u32 v6, v5, 16, 1
	v_add3_u32 v5, v5, v6, s82
	ds_write_b16_d16_hi v2, v5 offset:9280
	v_bfe_u32 v5, v4, 16, 1
	v_add3_u32 v4, v4, v5, s82
	ds_write_b16_d16_hi v2, v4 offset:26688
	v_add_f32_e32 v4, v143, v124
	v_mul_f32_e32 v5, 0x3fb8aa3b, v4
	v_exp_f32_e32 v5, v5
	v_mul_f32_e32 v4, 0xbfb8aa3b, v4
	v_exp_f32_e32 v4, v4
	v_lshlrev_b32_e32 v6, 16, v30
	v_mul_f32_e32 v5, v5, v6
	v_mul_f32_e32 v5, 0x3db504f3, v5
	v_lshlrev_b32_e32 v6, 16, v28
	v_mul_f32_e32 v4, v4, v6
	v_bfe_u32 v6, v5, 16, 1
	v_add3_u32 v5, v5, v6, s82
	ds_write_b16_d16_hi v2, v5 offset:9552
	v_bfe_u32 v5, v4, 16, 1
	v_add3_u32 v4, v4, v5, s82
	ds_write_b16_d16_hi v2, v4 offset:26960
	v_add_f32_e32 v4, v144, v124
	v_mul_f32_e32 v5, 0x3fb8aa3b, v4
	v_exp_f32_e32 v5, v5
	v_mul_f32_e32 v4, 0xbfb8aa3b, v4
	v_exp_f32_e32 v4, v4
	v_lshlrev_b32_e32 v6, 16, v27
	v_mul_f32_e32 v5, v5, v6
	v_mul_f32_e32 v5, 0x3db504f3, v5
	v_lshlrev_b32_e32 v6, 16, v25
	v_mul_f32_e32 v4, v4, v6
	v_bfe_u32 v6, v5, 16, 1
	v_add3_u32 v5, v5, v6, s82
	ds_write_b16_d16_hi v2, v5 offset:9824
	v_bfe_u32 v5, v4, 16, 1
	v_add3_u32 v4, v4, v5, s82
	ds_write_b16_d16_hi v2, v4 offset:27232
	v_add_f32_e32 v4, v145, v124
	v_mul_f32_e32 v5, 0x3fb8aa3b, v4
	v_exp_f32_e32 v5, v5
	v_mul_f32_e32 v4, 0xbfb8aa3b, v4
	v_exp_f32_e32 v4, v4
	v_lshlrev_b32_e32 v6, 16, v26
	v_mul_f32_e32 v5, v5, v6
	v_mul_f32_e32 v5, 0x3db504f3, v5
	v_lshlrev_b32_e32 v6, 16, v24
	v_mul_f32_e32 v4, v4, v6
	v_bfe_u32 v6, v5, 16, 1
	v_add3_u32 v5, v5, v6, s82
	ds_write_b16_d16_hi v2, v5 offset:10096
	v_bfe_u32 v5, v4, 16, 1
	v_add3_u32 v4, v4, v5, s82
	ds_write_b16_d16_hi v2, v4 offset:27504
	v_add_f32_e32 v4, v146, v124
	v_mul_f32_e32 v5, 0x3fb8aa3b, v4
	v_exp_f32_e32 v5, v5
	v_mul_f32_e32 v4, 0xbfb8aa3b, v4
	v_exp_f32_e32 v4, v4
	v_lshlrev_b32_e32 v6, 16, v23
	v_mul_f32_e32 v5, v5, v6
	v_mul_f32_e32 v5, 0x3db504f3, v5
	v_lshlrev_b32_e32 v6, 16, v22
	v_mul_f32_e32 v4, v4, v6
	v_bfe_u32 v6, v5, 16, 1
	v_add3_u32 v5, v5, v6, s82
	ds_write_b16_d16_hi v2, v5 offset:10368
	v_bfe_u32 v5, v4, 16, 1
	v_add3_u32 v4, v4, v5, s82
	ds_write_b16_d16_hi v2, v4 offset:27776
	v_add_f32_e32 v4, v147, v124
	v_mul_f32_e32 v5, 0x3fb8aa3b, v4
	v_exp_f32_e32 v5, v5
	v_mul_f32_e32 v4, 0xbfb8aa3b, v4
	v_exp_f32_e32 v4, v4
	v_lshlrev_b32_e32 v6, 16, v17
	v_mul_f32_e32 v5, v5, v6
	v_mul_f32_e32 v5, 0x3db504f3, v5
	v_lshlrev_b32_e32 v6, 16, v16
	v_mul_f32_e32 v4, v4, v6
	v_bfe_u32 v6, v5, 16, 1
	v_add3_u32 v5, v5, v6, s82
	ds_write_b16_d16_hi v2, v5 offset:10640
	v_bfe_u32 v5, v4, 16, 1
	v_add3_u32 v4, v4, v5, s82
	ds_write_b16_d16_hi v2, v4 offset:28048
	v_add_f32_e32 v4, v148, v124
	v_mul_f32_e32 v5, 0x3fb8aa3b, v4
	v_exp_f32_e32 v5, v5
	v_mul_f32_e32 v4, 0xbfb8aa3b, v4
; #define LAS __attribute__((address_space(3)))
; __device__ __forceinline__ float bf2f(unsigned u) { return __uint_as_float(u << 16); }
; __device__ __forceinline__ unsigned f2bf(float f) { unsigned u = __float_as_uint(f); return (u + 0x7fffu + ((u >> 16) & 1u)) >> 16; }
; #define MFMA32(a, b, c) __builtin_amdgcn_mfma_f32_32x32x16_bf16((a), (b), (c), 0, 0, 0)
; template <int MODE> __device__ __forceinline__ void gla_item(const Args& a, LAS unsigned char* lds, int cid, int h, GlaPre& pf, int next) {
;     ...
;         for (int i = 0; i < 16; ++i) { const float b = bc[i] + off; const int t = 16 * tg + i;
;             const float qe = bf2f(qraw[i]) * __expf(b) * 0.08838834764831845f, ke = bf2f(kraw[i]) * __expf(-b);
;             QE[t * QES + dk] = (bf16_t)f2bf(qe); KE[t * QES + dk] = (bf16_t)f2bf(ke); }
;     }
;     __syncthreads();
;     ...
;         u32x2 rraw[8];
; #pragma unroll
;         for (int i = 0; i < 8; ++i) rraw[i] = *(const u32x2*)(P + (size_t)(8 * w + i) * NPJ + 2048 + h * 256 + 4 * lane);
;         f32x16 o[2]; o[0] = f32x16{}; o[1] = f32x16{};
; #pragma unroll
;         for (int tb = 0; tb < 2; ++tb)
; #pragma unroll
;             for (int ks = 0; ks < 8; ++ks) { const bf16x8 qa = *(const LAS bf16x8*)(QE + (32 * tb + l31) * QES + 16 * ks + 8 * hi); o[tb] = MFMA32(qa, sfr[ks], o[tb]); }
	v_exp_f32_e32 v4, v4
	v_lshlrev_b32_e32 v6, 16, v15
	v_mul_f32_e32 v5, v5, v6
	v_mul_f32_e32 v5, 0x3db504f3, v5
	v_lshlrev_b32_e32 v6, 16, v13
	v_mul_f32_e32 v4, v4, v6
	v_bfe_u32 v6, v5, 16, 1
	v_add3_u32 v5, v5, v6, s82
	ds_write_b16_d16_hi v2, v5 offset:10912
	v_bfe_u32 v5, v4, 16, 1
	v_add3_u32 v4, v4, v5, s82
	ds_write_b16_d16_hi v2, v4 offset:28320
	v_add_f32_e32 v4, v149, v124
	v_mul_f32_e32 v5, 0x3fb8aa3b, v4
	v_exp_f32_e32 v5, v5
	v_mul_f32_e32 v4, 0xbfb8aa3b, v4
	v_exp_f32_e32 v4, v4
	v_lshlrev_b32_e32 v6, 16, v14
	v_mul_f32_e32 v5, v5, v6
	v_mul_f32_e32 v5, 0x3db504f3, v5
	v_lshlrev_b32_e32 v6, 16, v12
	v_mul_f32_e32 v4, v4, v6
	v_bfe_u32 v6, v5, 16, 1
	v_add3_u32 v5, v5, v6, s82
	ds_write_b16_d16_hi v2, v5 offset:11184
	v_bfe_u32 v5, v4, 16, 1
	v_add3_u32 v4, v4, v5, s82
	ds_write_b16_d16_hi v2, v4 offset:28592
	v_add_f32_e32 v4, v150, v124
	v_mul_f32_e32 v5, 0x3fb8aa3b, v4
	v_exp_f32_e32 v5, v5
	v_mul_f32_e32 v4, 0xbfb8aa3b, v4
	v_exp_f32_e32 v4, v4
	v_lshlrev_b32_e32 v6, 16, v11
	v_mul_f32_e32 v5, v5, v6
	v_mul_f32_e32 v5, 0x3db504f3, v5
	v_lshlrev_b32_e32 v6, 16, v10
	v_mul_f32_e32 v4, v4, v6
	v_bfe_u32 v6, v5, 16, 1
	v_add3_u32 v5, v5, v6, s82
	ds_write_b16_d16_hi v2, v5 offset:11456
	v_bfe_u32 v5, v4, 16, 1
	v_add3_u32 v4, v4, v5, s82
	ds_write_b16_d16_hi v2, v4 offset:28864
	v_add_f32_e32 v4, v84, v124
	v_mul_f32_e32 v5, 0x3fb8aa3b, v4
	v_exp_f32_e32 v5, v5
	v_mul_f32_e32 v4, 0xbfb8aa3b, v4
	v_exp_f32_e32 v4, v4
	v_lshlrev_b32_e32 v6, 16, v9
	v_mul_f32_e32 v5, v5, v6
	v_mul_f32_e32 v5, 0x3db504f3, v5
	v_lshlrev_b32_e32 v6, 16, v8
	v_mul_f32_e32 v4, v4, v6
	v_bfe_u32 v6, v5, 16, 1
	v_add3_u32 v5, v5, v6, s82
	ds_write_b16_d16_hi v2, v5 offset:11728
	v_bfe_u32 v5, v4, 16, 1
	v_add3_u32 v4, v4, v5, s82
	ds_write_b16_d16_hi v2, v4 offset:29136
	v_add_f32_e32 v4, v85, v124
	v_mul_f32_e32 v5, 0x3fb8aa3b, v4
	v_exp_f32_e32 v5, v5
	v_mul_f32_e32 v4, 0xbfb8aa3b, v4
	v_exp_f32_e32 v4, v4
	v_lshlrev_b32_e32 v6, 16, v7
	v_mul_f32_e32 v5, v5, v6
	v_mul_f32_e32 v5, 0x3db504f3, v5
	v_lshlrev_b32_e32 v3, 16, v3
	v_mul_f32_e32 v3, v4, v3
	v_bfe_u32 v4, v5, 16, 1
	v_add3_u32 v4, v5, v4, s82
	ds_write_b16_d16_hi v2, v4 offset:12000
	v_bfe_u32 v4, v3, 16, 1
	v_add3_u32 v3, v3, v4, s82
	ds_write_b16_d16_hi v2, v3 offset:29408
	v_mul_u32_u24_e32 v2, 0x110, v74
	v_add3_u32 v73, 0, v76, v2
	s_waitcnt lgkmcnt(0)
	s_barrier
	ds_read_b128 v[170:173], v73 offset:8192
	ds_read_b128 v[174:177], v73 offset:8224
	ds_read_b128 v[178:181], v73 offset:8256
	ds_read_b128 v[182:185], v73 offset:8288
	ds_read_b128 v[186:189], v73 offset:8320
	ds_read_b128 v[190:193], v73 offset:8352
	ds_read_b128 v[194:197], v73 offset:8384
	ds_read_b128 v[198:201], v73 offset:8416
	ds_read_b128 v[202:205], v73 offset:16896
	ds_read_b128 v[206:209], v73 offset:16928
	ds_read_b128 v[210:213], v73 offset:16960
	ds_read_b128 v[214:217], v73 offset:16992
	ds_read_b128 v[218:221], v73 offset:17024
	ds_read_b128 v[222:225], v73 offset:17056
	s_lshl_b32 s59, s86, 3
	s_mul_i32 s0, s86, 0xc000
	s_mul_hi_i32 s1, s59, 0x1800
	s_add_u32 s0, s68, s0
	s_addc_u32 s1, s69, s1
	s_lshl_b32 s87, s87, 9
	s_add_u32 s0, s0, s87
	s_addc_u32 s1, s1, 0
	v_lshlrev_b32_e32 v66, 3, v123
	v_lshl_add_u64 v[6:7], s[0:1], 0, v[66:67]
	v_add_co_u32_e32 v30, vcc, s35, v6
	s_or_b32 s58, s59, 1
	s_nop 0
	v_addc_co_u32_e32 v31, vcc, 0, v7, vcc
	s_waitcnt lgkmcnt(13)
	ds_read_b128 v[226:229], v73 offset:17088
	v_mfma_f32_32x32x16_bf16 v[2:17], v[170:173], v[18:21], 0
	s_mul_i32 s1, s58, 0x1800
	s_mul_hi_i32 s0, s58, 0x1800
	s_add_u32 s1, s68, s1
	s_addc_u32 s52, s69, s0
	s_add_u32 s0, s1, s87
	s_addc_u32 s1, s52, 0
	s_waitcnt lgkmcnt(13)
	ds_read_b128 v[230:233], v73 offset:17120
	v_mfma_f32_32x32x16_bf16 v[2:17], v[174:177], v[34:37], v[2:17]
	v_lshl_add_u64 v[22:23], s[0:1], 0, v[66:67]
	v_add_co_u32_e32 v32, vcc, s35, v22
	s_or_b32 s57, s59, 2
	s_nop 0
	v_addc_co_u32_e32 v33, vcc, 0, v23, vcc
	s_waitcnt lgkmcnt(13)
	v_mfma_f32_32x32x16_bf16 v[2:17], v[178:181], v[38:41], v[2:17]
	s_mul_i32 s1, s57, 0x1800
	s_mul_hi_i32 s0, s57, 0x1800
	s_add_u32 s1, s68, s1
	s_addc_u32 s52, s69, s0
	s_add_u32 s0, s1, s87
	s_addc_u32 s1, s52, 0
	s_waitcnt lgkmcnt(12)
	v_mfma_f32_32x32x16_bf16 v[2:17], v[182:185], v[42:45], v[2:17]
	v_lshl_add_u64 v[22:23], s[0:1], 0, v[66:67]
	v_add_co_u32_e32 v78, vcc, s35, v22
	s_or_b32 s56, s59, 3
	s_nop 0
	v_addc_co_u32_e32 v79, vcc, 0, v23, vcc
	s_waitcnt lgkmcnt(11)
	v_mfma_f32_32x32x16_bf16 v[2:17], v[186:189], v[46:49], v[2:17]
	s_mul_i32 s1, s56, 0x1800
	s_mul_hi_i32 s0, s56, 0x1800
	s_add_u32 s1, s68, s1
	s_addc_u32 s52, s69, s0
	s_add_u32 s0, s1, s87
	s_addc_u32 s1, s52, 0
	v_lshl_add_u64 v[26:27], s[0:1], 0, v[66:67]
	s_waitcnt lgkmcnt(10)
	v_mfma_f32_32x32x16_bf16 v[2:17], v[190:193], v[54:57], v[2:17]
	v_add_co_u32_e32 v26, vcc, s35, v26
	s_or_b32 s55, s59, 4
	s_nop 0
	v_addc_co_u32_e32 v27, vcc, 0, v27, vcc
	global_load_dwordx2 v[84:85], v[30:31], off
	global_load_dwordx2 v[82:83], v[32:33], off
	global_load_dwordx2 v[80:81], v[78:79], off
	s_nop 0
	global_load_dwordx2 v[78:79], v[26:27], off
	s_waitcnt lgkmcnt(9)
	v_mfma_f32_32x32x16_bf16 v[2:17], v[194:197], v[58:61], v[2:17]
	s_mul_i32 s1, s55, 0x1800
	s_mul_hi_i32 s0, s55, 0x1800
	s_add_u32 s1, s68, s1
	s_addc_u32 s52, s69, s0
	s_add_u32 s0, s1, s87
	s_addc_u32 s1, s52, 0
	s_waitcnt lgkmcnt(8)
	v_mfma_f32_32x32x16_bf16 v[2:17], v[198:201], v[62:65], v[2:17]
	v_lshl_add_u64 v[26:27], s[0:1], 0, v[66:67]
	v_add_co_u32_e32 v132, vcc, s35, v26
	v_addc_co_u32_e32 v133, vcc, 0, v27, vcc
	s_waitcnt lgkmcnt(7)
; #define LAS __attribute__((address_space(3)))
; #define MFMA32(a, b, c) __builtin_amdgcn_mfma_f32_32x32x16_bf16((a), (b), (c), 0, 0, 0)
; template <int MODE> __device__ __forceinline__ void gla_item(const Args& a, LAS unsigned char* lds, int cid, int h, GlaPre& pf, int next) {
;     ...
;         u32x2 rraw[8];
; #pragma unroll
;         for (int i = 0; i < 8; ++i) rraw[i] = *(const u32x2*)(P + (size_t)(8 * w + i) * NPJ + 2048 + h * 256 + 4 * lane);
;         f32x16 o[2]; o[0] = f32x16{}; o[1] = f32x16{};
; #pragma unroll
;         for (int tb = 0; tb < 2; ++tb)
; #pragma unroll
;             for (int ks = 0; ks < 8; ++ks) { const bf16x8 qa = *(const LAS bf16x8*)(QE + (32 * tb + l31) * QES + 16 * ks + 8 * hi); o[tb] = MFMA32(qa, sfr[ks], o[tb]); }
;         if (w < 3) {
	v_mfma_f32_32x32x16_bf16 v[18:33], v[202:205], v[18:21], 0
	s_or_b32 s54, s59, 5
	s_mul_i32 s1, s54, 0x1800
	s_mul_hi_i32 s0, s54, 0x1800
	s_add_u32 s1, s68, s1
	s_addc_u32 s52, s69, s0
	s_add_u32 s0, s1, s87
	s_addc_u32 s1, s52, 0
	s_waitcnt lgkmcnt(6)
	v_mfma_f32_32x32x16_bf16 v[18:33], v[206:209], v[34:37], v[18:33]
	v_lshl_add_u64 v[34:35], s[0:1], 0, v[66:67]
	v_add_co_u32_e32 v124, vcc, s35, v34
	s_or_b32 s53, s59, 6
	s_nop 0
	v_addc_co_u32_e32 v125, vcc, 0, v35, vcc
	s_waitcnt lgkmcnt(5)
	v_mfma_f32_32x32x16_bf16 v[18:33], v[210:213], v[38:41], v[18:33]
	s_mul_i32 s1, s53, 0x1800
	s_mul_hi_i32 s0, s53, 0x1800
	s_add_u32 s1, s68, s1
	s_addc_u32 s52, s69, s0
	s_add_u32 s0, s1, s87
	s_addc_u32 s1, s52, 0
	s_waitcnt lgkmcnt(4)
	v_mfma_f32_32x32x16_bf16 v[18:33], v[214:217], v[42:45], v[18:33]
	v_lshl_add_u64 v[34:35], s[0:1], 0, v[66:67]
	v_add_co_u32_e32 v42, vcc, s35, v34
	s_or_b32 s52, s59, 7
	s_nop 0
	v_addc_co_u32_e32 v43, vcc, 0, v35, vcc
	s_waitcnt lgkmcnt(3)
	v_mfma_f32_32x32x16_bf16 v[18:33], v[218:221], v[46:49], v[18:33]
	s_mul_i32 s1, s52, 0x1800
	s_mul_hi_i32 s0, s52, 0x1800
	s_add_u32 s1, s68, s1
	s_addc_u32 s68, s69, s0
	s_add_u32 s0, s1, s87
	s_addc_u32 s1, s68, 0
	s_waitcnt lgkmcnt(2)
	v_mfma_f32_32x32x16_bf16 v[18:33], v[222:225], v[54:57], v[18:33]
	v_lshl_add_u64 v[34:35], s[0:1], 0, v[66:67]
	v_add_co_u32_e32 v44, vcc, s35, v34
	s_mov_b64 s[0:1], -1
	s_nop 0
	v_addc_co_u32_e32 v45, vcc, 0, v35, vcc
	s_waitcnt lgkmcnt(1)
	v_mfma_f32_32x32x16_bf16 v[18:33], v[226:229], v[58:61], v[18:33]
	global_load_dwordx2 v[60:61], v[132:133], off
	global_load_dwordx2 v[58:59], v[124:125], off
	global_load_dwordx2 v[56:57], v[42:43], off
	global_load_dwordx2 v[54:55], v[44:45], off
	s_cmp_lt_i32 s86, 3
	s_waitcnt lgkmcnt(0)
	v_mfma_f32_32x32x16_bf16 v[18:33], v[230:233], v[62:65], v[18:33]
	v_lshlrev_b32_e32 v62, 3, v122
	s_cbranch_scc1 .LBB0_718
	v_lshlrev_b32_e32 v34, 3, v122
	s_mov_b64 s[0:1], 0
; #define LAS __attribute__((address_space(3)))
; __device__ __forceinline__ unsigned f2bf(float f) { unsigned u = __float_as_uint(f); return (u + 0x7fffu + ((u >> 16) & 1u)) >> 16; }
; __device__ __forceinline__ int crow(int r, int hi) { return (r & 3) + 8 * (r >> 2) + 4 * hi; }
; #define MFMA32(a, b, c) __builtin_amdgcn_mfma_f32_32x32x16_bf16((a), (b), (c), 0, 0, 0)
; template <int MODE> __device__ __forceinline__ void gla_item(const Args& a, LAS unsigned char* lds, int cid, int h, GlaPre& pf, int next) {
;     ...
;         if (w < 3) {
;             const int tb = (w > 0) ? 1 : 0, sb = (w == 2) ? 1 : 0;
;             f32x16 am = f32x16{};
; #pragma unroll
;             for (int ks = 0; ks < 8; ++ks) { const bf16x8 qa = *(const LAS bf16x8*)(QE + (32 * tb + l31) * QES + 16 * ks + 8 * hi), kb = *(const LAS bf16x8*)(KE + (32 * sb + l31) * QES + 16 * ks + 8 * hi);
;                 am = MFMA32(qa, kb, am); }
; #pragma unroll
;             for (int r = 0; r < 16; ++r) { const int tl = crow(r, hi); float v = am[r]; if (tb == sb && l31 > tl) v = 0.f; AL[(32 * tb + tl) * VTS + 32 * sb + l31] = (bf16_t)f2bf(v); }
;         }
.LBB0_718:
	s_andn2_b64 vcc, exec, s[0:1]
	s_cbranch_vccnz .LBB0_699
	s_cmp_lt_i32 s86, 1
	s_cselect_b64 s[0:1], -1, 0
	s_and_b64 s[68:69], s[0:1], exec
	s_cselect_b32 s87, 0, 32
	s_cmp_eq_u32 s86, 2
	s_cselect_b64 s[68:69], -1, 0
	v_or_b32_e32 v34, s87, v74
	s_and_b64 s[88:89], s[68:69], exec
	v_mul_u32_u24_e32 v34, 0x110, v34
	s_cselect_b32 s88, 32, 0
	v_add3_u32 v63, 0, v34, v76
	v_or_b32_e32 v34, s88, v74
	v_mul_u32_u24_e32 v34, 0x110, v34
	v_add3_u32 v64, 0, v34, v76
	ds_read_b128 v[170:173], v63 offset:8192
	ds_read_b128 v[174:177], v63 offset:8224
	ds_read_b128 v[178:181], v64 offset:25600
	ds_read_b128 v[182:185], v64 offset:25632
	ds_read_b128 v[186:189], v63 offset:8256
	ds_read_b128 v[190:193], v64 offset:25664
	ds_read_b128 v[194:197], v63 offset:8288
	ds_read_b128 v[198:201], v64 offset:25696
	ds_read_b128 v[202:205], v63 offset:8320
	ds_read_b128 v[206:209], v64 offset:25728
	ds_read_b128 v[210:213], v63 offset:8352
	ds_read_b128 v[214:217], v64 offset:25760
	ds_read_b128 v[218:221], v63 offset:8384
	ds_read_b128 v[222:225], v64 offset:25792
	s_waitcnt lgkmcnt(11)
	ds_read_b128 v[226:229], v63 offset:8416
	ds_read_b128 v[230:233], v64 offset:25824
	v_mfma_f32_32x32x16_bf16 v[34:49], v[170:173], v[178:181], 0
	s_or_b64 s[0:1], s[0:1], s[68:69]
	s_lshl_b32 s68, s88, 1
	s_add_i32 s68, s68, 0
	s_add_i32 s68, s68, 0x13800
	s_waitcnt lgkmcnt(12)
	v_mfma_f32_32x32x16_bf16 v[34:49], v[174:177], v[182:185], v[34:49]
	s_waitcnt lgkmcnt(10)
	v_mfma_f32_32x32x16_bf16 v[34:49], v[186:189], v[190:193], v[34:49]
	s_waitcnt lgkmcnt(8)
	v_mfma_f32_32x32x16_bf16 v[34:49], v[194:197], v[198:201], v[34:49]
	s_waitcnt lgkmcnt(6)
	v_mfma_f32_32x32x16_bf16 v[34:49], v[202:205], v[206:209], v[34:49]
	s_waitcnt lgkmcnt(4)
	v_mfma_f32_32x32x16_bf16 v[34:49], v[210:213], v[214:217], v[34:49]
	s_waitcnt lgkmcnt(2)
	v_mfma_f32_32x32x16_bf16 v[34:49], v[218:221], v[222:225], v[34:49]
	v_lshlrev_b32_e32 v63, 2, v122
	v_cmp_gt_u32_e32 vcc, v74, v63
	v_lshl_add_u32 v64, v74, 1, s68
	s_and_b64 s[68:69], s[0:1], vcc
	s_waitcnt lgkmcnt(0)
	v_mfma_f32_32x32x16_bf16 v[34:49], v[226:229], v[230:233], v[34:49]
	s_nop 11
	v_cndmask_b32_e64 v34, v34, 0, s[68:69]
	v_bfe_u32 v65, v34, 16, 1
	v_add3_u32 v34, v34, v65, s82
	v_or_b32_e32 v65, s87, v63
	v_mad_u32_u24 v65, v65, s77, v64
	ds_write_b16_d16_hi v65, v34
	v_or_b32_e32 v34, 1, v63
	v_cmp_gt_u32_e32 vcc, v74, v34
	s_and_b64 s[68:69], s[0:1], vcc
	v_cndmask_b32_e64 v35, v35, 0, s[68:69]
	v_bfe_u32 v65, v35, 16, 1
	v_or_b32_e32 v34, s87, v34
	v_add3_u32 v35, v35, v65, s82
	v_mad_u32_u24 v34, v34, s77, v64
	ds_write_b16_d16_hi v34, v35
	v_or_b32_e32 v34, 2, v63
	v_cmp_gt_u32_e32 vcc, v74, v34
	s_and_b64 s[68:69], s[0:1], vcc
	v_cndmask_b32_e64 v35, v36, 0, s[68:69]
	v_bfe_u32 v36, v35, 16, 1
	v_or_b32_e32 v34, s87, v34
	v_add3_u32 v35, v35, v36, s82
	v_mad_u32_u24 v34, v34, s77, v64
	ds_write_b16_d16_hi v34, v35
	v_or_b32_e32 v34, 3, v63
	v_cmp_gt_u32_e32 vcc, v74, v34
	s_and_b64 s[68:69], s[0:1], vcc
	v_cndmask_b32_e64 v35, v37, 0, s[68:69]
	v_bfe_u32 v36, v35, 16, 1
	v_or_b32_e32 v34, s87, v34
	v_add3_u32 v35, v35, v36, s82
	v_mad_u32_u24 v34, v34, s77, v64
	ds_write_b16_d16_hi v34, v35
	v_or_b32_e32 v34, 8, v63
	v_cmp_gt_u32_e32 vcc, v74, v34
	s_and_b64 s[68:69], s[0:1], vcc
	v_cndmask_b32_e64 v35, v38, 0, s[68:69]
	v_bfe_u32 v36, v35, 16, 1
	v_or_b32_e32 v34, s87, v34
	v_add3_u32 v35, v35, v36, s82
	v_mad_u32_u24 v34, v34, s77, v64
	ds_write_b16_d16_hi v34, v35
	v_or_b32_e32 v34, 9, v63
	v_cmp_gt_u32_e32 vcc, v74, v34
	s_and_b64 s[68:69], s[0:1], vcc
	v_cndmask_b32_e64 v35, v39, 0, s[68:69]
	v_bfe_u32 v36, v35, 16, 1
	v_or_b32_e32 v34, s87, v34
	v_add3_u32 v35, v35, v36, s82
	v_mad_u32_u24 v34, v34, s77, v64
	ds_write_b16_d16_hi v34, v35
	v_or_b32_e32 v34, 10, v63
	v_cmp_gt_u32_e32 vcc, v74, v34
	s_and_b64 s[68:69], s[0:1], vcc
	v_cndmask_b32_e64 v35, v40, 0, s[68:69]
	v_bfe_u32 v36, v35, 16, 1
	v_or_b32_e32 v34, s87, v34
	v_add3_u32 v35, v35, v36, s82
	v_mad_u32_u24 v34, v34, s77, v64
	ds_write_b16_d16_hi v34, v35
	v_or_b32_e32 v34, 11, v63
	v_cmp_gt_u32_e32 vcc, v74, v34
	s_and_b64 s[68:69], s[0:1], vcc
	v_cndmask_b32_e64 v35, v41, 0, s[68:69]
	v_bfe_u32 v36, v35, 16, 1
	v_or_b32_e32 v34, s87, v34
	v_add3_u32 v35, v35, v36, s82
	v_mad_u32_u24 v34, v34, s77, v64
	ds_write_b16_d16_hi v34, v35
	v_or_b32_e32 v34, 16, v63
	v_cmp_gt_u32_e32 vcc, v74, v34
	s_and_b64 s[68:69], s[0:1], vcc
	v_cndmask_b32_e64 v35, v42, 0, s[68:69]
	v_bfe_u32 v36, v35, 16, 1
	v_or_b32_e32 v34, s87, v34
	v_add3_u32 v35, v35, v36, s82
	v_mad_u32_u24 v34, v34, s77, v64
	ds_write_b16_d16_hi v34, v35
	v_or_b32_e32 v34, 17, v63
	v_cmp_gt_u32_e32 vcc, v74, v34
	s_and_b64 s[68:69], s[0:1], vcc
	v_cndmask_b32_e64 v35, v43, 0, s[68:69]
	v_bfe_u32 v36, v35, 16, 1
	v_or_b32_e32 v34, s87, v34
	v_add3_u32 v35, v35, v36, s82
	v_mad_u32_u24 v34, v34, s77, v64
	ds_write_b16_d16_hi v34, v35
	v_or_b32_e32 v34, 18, v63
	v_cmp_gt_u32_e32 vcc, v74, v34
	s_and_b64 s[68:69], s[0:1], vcc
	v_cndmask_b32_e64 v35, v44, 0, s[68:69]
	v_bfe_u32 v36, v35, 16, 1
	v_or_b32_e32 v34, s87, v34
	v_add3_u32 v35, v35, v36, s82
	v_mad_u32_u24 v34, v34, s77, v64
	ds_write_b16_d16_hi v34, v35
	v_or_b32_e32 v34, 19, v63
	v_cmp_gt_u32_e32 vcc, v74, v34
	s_and_b64 s[68:69], s[0:1], vcc
	v_cndmask_b32_e64 v35, v45, 0, s[68:69]
	v_bfe_u32 v36, v35, 16, 1
	v_or_b32_e32 v34, s87, v34
	v_add3_u32 v35, v35, v36, s82
	v_mad_u32_u24 v34, v34, s77, v64
	ds_write_b16_d16_hi v34, v35
	v_or_b32_e32 v34, 24, v63
	v_cmp_gt_u32_e32 vcc, v74, v34
	s_and_b64 s[68:69], s[0:1], vcc
	v_cndmask_b32_e64 v35, v46, 0, s[68:69]
	v_bfe_u32 v36, v35, 16, 1
	v_or_b32_e32 v34, s87, v34
	v_add3_u32 v35, v35, v36, s82
	v_mad_u32_u24 v34, v34, s77, v64
	ds_write_b16_d16_hi v34, v35
	v_or_b32_e32 v34, 25, v63
	v_cmp_gt_u32_e32 vcc, v74, v34
	s_and_b64 s[68:69], s[0:1], vcc
	v_cndmask_b32_e64 v35, v47, 0, s[68:69]
	v_bfe_u32 v36, v35, 16, 1
	v_or_b32_e32 v34, s87, v34
	v_add3_u32 v35, v35, v36, s82
	v_mad_u32_u24 v34, v34, s77, v64
	ds_write_b16_d16_hi v34, v35
	v_or_b32_e32 v34, 26, v63
	v_cmp_gt_u32_e32 vcc, v74, v34
	s_and_b64 s[68:69], s[0:1], vcc
	v_cndmask_b32_e64 v35, v48, 0, s[68:69]
	v_bfe_u32 v36, v35, 16, 1
	v_or_b32_e32 v34, s87, v34
	v_add3_u32 v35, v35, v36, s82
	v_mad_u32_u24 v34, v34, s77, v64
	ds_write_b16_d16_hi v34, v35
	v_or_b32_e32 v34, 27, v63
	v_cmp_gt_u32_e32 vcc, v74, v34
	s_and_b64 s[0:1], s[0:1], vcc
	v_cndmask_b32_e64 v35, v49, 0, s[0:1]
	v_bfe_u32 v36, v35, 16, 1
	v_or_b32_e32 v34, s87, v34
	v_add3_u32 v35, v35, v36, s82
	v_mad_u32_u24 v34, v34, s77, v64
	ds_write_b16_d16_hi v34, v35
	v_mov_b32_e32 v34, v62
	s_branch .LBB0_699

; #define LAS __attribute__((address_space(3)))
; __device__ __forceinline__ unsigned pk(float lo, float hi) { return pg8::cvt_pk_bf16(lo, hi); }
; #define MFMA32(a, b, c) __builtin_amdgcn_mfma_f32_32x32x16_bf16((a), (b), (c), 0, 0, 0)
; template <bool QLDS> __device__ __forceinline__ void attn_tile(const LAS unsigned char* buf, const bf16x8 (&qf)[4], const LAS bf16x8* qlds, float cq2, int qpos, int kv0, bool diag, float& mrun, float& lrun, f32x16 (&ot)[2], int l31, int hi) {
;     ...
;     float rs = 0.f;
; #pragma unroll
;     for (int r = 0; r < 16; ++r) { p0[r] = __builtin_amdgcn_exp2f(p0[r] - mrun); p1[r] = __builtin_amdgcn_exp2f(p1[r] - mrun); rs += p0[r] + p1[r]; }
;     lrun += rs;
;     bf16x8 pf[4];
;     { u32x4 x; x.x = pk(p0[0], p0[1]); x.y = pk(p0[2], p0[3]); x.z = pk(p0[4], p0[5]); x.w = pk(p0[6], p0[7]); pf[0] = __builtin_bit_cast(bf16x8, x);
;       x.x = pk(p0[8], p0[9]); x.y = pk(p0[10], p0[11]); x.z = pk(p0[12], p0[13]); x.w = pk(p0[14], p0[15]); pf[1] = __builtin_bit_cast(bf16x8, x);
;       x.x = pk(p1[0], p1[1]); x.y = pk(p1[2], p1[3]); x.z = pk(p1[4], p1[5]); x.w = pk(p1[6], p1[7]); pf[2] = __builtin_bit_cast(bf16x8, x);
;       x.x = pk(p1[8], p1[9]); x.y = pk(p1[10], p1[11]); x.z = pk(p1[12], p1[13]); x.w = pk(p1[14], p1[15]); pf[3] = __builtin_bit_cast(bf16x8, x); }
;     __builtin_amdgcn_sched_barrier(0);
; #pragma unroll
;     for (int db = 0; db < 2; ++db)
; #pragma unroll
;         for (int ks = 0; ks < 4; ++ks) { const LAS bf16_t* vp = VTs + (32 * db + l31) * AT_VS + 16 * ks + 4 * hi;
;             const u32x2 lo = *(const LAS u32x2*)vp, hh2 = *(const LAS u32x2*)(vp + 8);
;             u32x4 x; x.x = lo.x; x.y = lo.y; x.z = hh2.x; x.w = hh2.y;
;             ot[db] = MFMA32(__builtin_bit_cast(bf16x8, x), pf[ks], ot[db]); }
.LBB0_1649:
	v_add3_u32 v217, s58, v110, v114
	v_add_u32_e32 v218, 0x2000, v217
	v_add_u32_e32 v217, 0x3000, v217
	ds_read2_b64 v[220:223], v218 offset0:128 offset1:130
	ds_read2_b64 v[224:227], v218 offset0:132 offset1:134
	ds_read2_b64 v[228:231], v218 offset0:136 offset1:138
	ds_read2_b64 v[232:235], v218 offset0:140 offset1:142
	ds_read2_b64 v[236:239], v217 offset0:160 offset1:162
	ds_read2_b64 v[240:243], v217 offset0:164 offset1:166
	ds_read2_b64 v[244:247], v217 offset0:168 offset1:170
	ds_read2_b64 v[248:251], v217 offset0:172 offset1:174
	v_sub_f32_e32 v50, v50, v66
	v_sub_f32_e32 v68, v68, v66
	v_exp_f32_e32 v151, v50
	v_sub_f32_e32 v50, v69, v66
	v_exp_f32_e32 v147, v68
	v_exp_f32_e32 v152, v50
	v_sub_f32_e32 v50, v51, v66
	v_sub_f32_e32 v52, v52, v66
	v_exp_f32_e32 v153, v50
	v_sub_f32_e32 v68, v70, v66
	v_exp_f32_e32 v155, v52
	v_sub_f32_e32 v52, v71, v66
	v_exp_f32_e32 v154, v68
	v_exp_f32_e32 v156, v52
	v_sub_f32_e32 v52, v53, v66
	v_exp_f32_e32 v157, v52
	v_add_f32_e32 v50, v147, v151
	v_add_f32_e32 v50, 0, v50
	v_add_f32_e32 v51, v152, v153
	v_add_f32_e32 v50, v51, v50
	v_add_f32_e32 v51, v154, v155
	v_add_f32_e32 v50, v51, v50
	v_add_f32_e32 v51, v156, v157
	v_add_f32_e32 v158, v51, v50
	v_sub_f32_e32 v50, v72, v66
	v_exp_f32_e32 v53, v50
	v_sub_f32_e32 v50, v54, v66
	v_exp_f32_e32 v69, v50
	v_sub_f32_e32 v50, v73, v66
	v_exp_f32_e32 v52, v50
	v_sub_f32_e32 v50, v55, v66
	v_exp_f32_e32 v68, v50
	v_sub_f32_e32 v50, v74, v66
	v_exp_f32_e32 v55, v50
	v_sub_f32_e32 v50, v56, v66
	v_exp_f32_e32 v71, v50
	v_sub_f32_e32 v50, v75, v66
	v_exp_f32_e32 v54, v50
	v_sub_f32_e32 v50, v57, v66
	v_exp_f32_e32 v70, v50
	v_pk_add_f32 v[50:51], v[52:53], v[68:69]
	s_nop 0
	v_add_f32_e32 v51, v51, v158
	v_add_f32_e32 v56, v50, v51
	v_pk_add_f32 v[50:51], v[54:55], v[70:71]
	s_nop 0
	v_add_f32_e32 v51, v51, v56
	v_add_f32_e32 v158, v50, v51
	v_sub_f32_e32 v50, v76, v66
	v_exp_f32_e32 v57, v50
	v_sub_f32_e32 v50, v58, v66
	v_exp_f32_e32 v73, v50
	v_sub_f32_e32 v50, v77, v66
	v_exp_f32_e32 v56, v50
	v_sub_f32_e32 v50, v59, v66
	v_exp_f32_e32 v72, v50
	v_sub_f32_e32 v50, v78, v66
	v_exp_f32_e32 v59, v50
	v_sub_f32_e32 v50, v60, v66
	v_exp_f32_e32 v75, v50
	v_sub_f32_e32 v50, v79, v66
	v_exp_f32_e32 v58, v50
	v_sub_f32_e32 v50, v61, v66
	v_exp_f32_e32 v74, v50
	v_pk_add_f32 v[50:51], v[56:57], v[72:73]
	s_nop 0
	v_add_f32_e32 v51, v51, v158
	v_add_f32_e32 v60, v50, v51
	v_pk_add_f32 v[50:51], v[58:59], v[74:75]
	s_nop 0
	v_add_f32_e32 v51, v51, v60
	v_add_f32_e32 v158, v50, v51
	v_sub_f32_e32 v50, v80, v66
	v_exp_f32_e32 v61, v50
	v_sub_f32_e32 v50, v62, v66
	v_exp_f32_e32 v77, v50
	v_sub_f32_e32 v50, v81, v66
	v_exp_f32_e32 v60, v50
	v_sub_f32_e32 v50, v63, v66
	v_exp_f32_e32 v76, v50
	v_sub_f32_e32 v50, v82, v66
	v_exp_f32_e32 v63, v50
	v_sub_f32_e32 v50, v64, v66
	v_exp_f32_e32 v79, v50
	v_sub_f32_e32 v50, v83, v66
	v_exp_f32_e32 v62, v50
	v_sub_f32_e32 v50, v65, v66
	v_exp_f32_e32 v78, v50
	v_pk_add_f32 v[50:51], v[60:61], v[76:77]
	s_nop 0
	v_add_f32_e32 v51, v51, v158
	v_add_f32_e32 v64, v50, v51
	v_pk_add_f32 v[50:51], v[62:63], v[78:79]
	s_nop 0
	v_add_f32_e32 v51, v51, v64
	v_add_f32_e32 v50, v50, v51
	v_add_f32_e32 v145, v145, v50
	v_cvt_pk_bf16_f32 v50, v147, v152
	v_cvt_pk_bf16_f32 v51, v154, v156
	v_cvt_pk_bf16_f32 v52, v53, v52
	v_cvt_pk_bf16_f32 v53, v55, v54
	v_cvt_pk_bf16_f32 v54, v57, v56
	v_cvt_pk_bf16_f32 v55, v59, v58
	v_cvt_pk_bf16_f32 v56, v61, v60
	v_cvt_pk_bf16_f32 v57, v63, v62
	v_cvt_pk_bf16_f32 v58, v151, v153
	v_cvt_pk_bf16_f32 v59, v155, v157
	v_cvt_pk_bf16_f32 v60, v69, v68
	v_cvt_pk_bf16_f32 v61, v71, v70
	v_cvt_pk_bf16_f32 v62, v73, v72
	v_cvt_pk_bf16_f32 v63, v75, v74
	v_cvt_pk_bf16_f32 v64, v77, v76
	v_cvt_pk_bf16_f32 v65, v79, v78
	s_waitcnt lgkmcnt(0)
	v_mfma_f32_32x32x16_bf16 v[18:33], v[220:223], v[50:53], v[18:33]
	v_mfma_f32_32x32x16_bf16 v[18:33], v[224:227], v[54:57], v[18:33]
	v_mfma_f32_32x32x16_bf16 v[18:33], v[228:231], v[58:61], v[18:33]
	v_mfma_f32_32x32x16_bf16 v[18:33], v[232:235], v[62:65], v[18:33]
	v_mfma_f32_32x32x16_bf16 v[2:17], v[236:239], v[50:53], v[2:17]
	v_mfma_f32_32x32x16_bf16 v[2:17], v[240:243], v[54:57], v[2:17]
	v_mfma_f32_32x32x16_bf16 v[2:17], v[244:247], v[58:61], v[2:17]
	v_mfma_f32_32x32x16_bf16 v[2:17], v[248:251], v[62:65], v[2:17]

; #define LAS __attribute__((address_space(3)))
; __device__ __forceinline__ unsigned pk(float lo, float hi) { return pg8::cvt_pk_bf16(lo, hi); }
; #define MFMA32(a, b, c) __builtin_amdgcn_mfma_f32_32x32x16_bf16((a), (b), (c), 0, 0, 0)
; template <bool QLDS> __device__ __forceinline__ void attn_tile(const LAS unsigned char* buf, const bf16x8 (&qf)[4], const LAS bf16x8* qlds, float cq2, int qpos, int kv0, bool diag, float& mrun, float& lrun, f32x16 (&ot)[2], int l31, int hi) {
;     ...
;     float rs = 0.f;
; #pragma unroll
;     for (int r = 0; r < 16; ++r) { p0[r] = __builtin_amdgcn_exp2f(p0[r] - mrun); p1[r] = __builtin_amdgcn_exp2f(p1[r] - mrun); rs += p0[r] + p1[r]; }
;     lrun += rs;
;     bf16x8 pf[4];
;     { u32x4 x; x.x = pk(p0[0], p0[1]); x.y = pk(p0[2], p0[3]); x.z = pk(p0[4], p0[5]); x.w = pk(p0[6], p0[7]); pf[0] = __builtin_bit_cast(bf16x8, x);
;       x.x = pk(p0[8], p0[9]); x.y = pk(p0[10], p0[11]); x.z = pk(p0[12], p0[13]); x.w = pk(p0[14], p0[15]); pf[1] = __builtin_bit_cast(bf16x8, x);
;       x.x = pk(p1[0], p1[1]); x.y = pk(p1[2], p1[3]); x.z = pk(p1[4], p1[5]); x.w = pk(p1[6], p1[7]); pf[2] = __builtin_bit_cast(bf16x8, x);
;       x.x = pk(p1[8], p1[9]); x.y = pk(p1[10], p1[11]); x.z = pk(p1[12], p1[13]); x.w = pk(p1[14], p1[15]); pf[3] = __builtin_bit_cast(bf16x8, x); }
;     __builtin_amdgcn_sched_barrier(0);
; #pragma unroll
;     for (int db = 0; db < 2; ++db)
; #pragma unroll
;         for (int ks = 0; ks < 4; ++ks) { const LAS bf16_t* vp = VTs + (32 * db + l31) * AT_VS + 16 * ks + 4 * hi;
;             const u32x2 lo = *(const LAS u32x2*)vp, hh2 = *(const LAS u32x2*)(vp + 8);
;             u32x4 x; x.x = lo.x; x.y = lo.y; x.z = hh2.x; x.w = hh2.y;
;             ot[db] = MFMA32(__builtin_bit_cast(bf16x8, x), pf[ks], ot[db]); }
.LBB0_1731:
	v_add3_u32 v217, s70, v147, v199
	v_add_u32_e32 v218, 0x2000, v217
	v_add_u32_e32 v217, 0x3000, v217
	ds_read2_b64 v[220:223], v218 offset0:128 offset1:130
	ds_read2_b64 v[224:227], v218 offset0:132 offset1:134
	ds_read2_b64 v[228:231], v218 offset0:136 offset1:138
	ds_read2_b64 v[232:235], v218 offset0:140 offset1:142
	ds_read2_b64 v[236:239], v217 offset0:160 offset1:162
	ds_read2_b64 v[240:243], v217 offset0:164 offset1:166
	ds_read2_b64 v[244:247], v217 offset0:168 offset1:170
	ds_read2_b64 v[248:251], v217 offset0:172 offset1:174
	v_sub_f32_e32 v68, v68, v129
	v_exp_f32_e32 v204, v68
	v_sub_f32_e32 v68, v84, v129
	v_exp_f32_e32 v205, v68
	v_sub_f32_e32 v68, v69, v129
	v_sub_f32_e32 v69, v85, v129
	v_exp_f32_e32 v68, v68
	v_exp_f32_e32 v84, v69
	v_add_f32_e32 v69, v204, v205
	v_mov_b32_e32 v85, v67
	v_pk_add_f32 v[202:203], v[68:69], v[84:85]
	v_sub_f32_e32 v69, v70, v129
	v_sub_f32_e32 v70, v86, v129
	v_pk_add_f32 v[202:203], v[202:203], v[202:203] op_sel_hi:[0,1]
	v_exp_f32_e32 v69, v69
	v_exp_f32_e32 v85, v70
	v_sub_f32_e32 v70, v71, v129
	v_sub_f32_e32 v71, v87, v129
	v_exp_f32_e32 v70, v70
	v_exp_f32_e32 v202, v71
	v_add_f32_e32 v71, v69, v85
	v_cvt_pk_bf16_f32 v68, v204, v68
	v_cvt_pk_bf16_f32 v69, v69, v70
	v_pk_add_f32 v[86:87], v[70:71], v[202:203]
	v_sub_f32_e32 v71, v72, v129
	v_sub_f32_e32 v72, v88, v129
	v_pk_add_f32 v[86:87], v[86:87], v[86:87] op_sel_hi:[0,1]
	v_exp_f32_e32 v71, v71
	v_exp_f32_e32 v203, v72
	v_sub_f32_e32 v72, v73, v129
	v_sub_f32_e32 v73, v89, v129
	v_exp_f32_e32 v72, v72
	v_exp_f32_e32 v86, v73
	v_add_f32_e32 v73, v71, v203
	v_cvt_pk_bf16_f32 v70, v71, v72
	v_pk_add_f32 v[88:89], v[72:73], v[86:87]
	v_sub_f32_e32 v73, v74, v129
	v_sub_f32_e32 v74, v90, v129
	v_pk_add_f32 v[88:89], v[88:89], v[88:89] op_sel_hi:[0,1]
	v_exp_f32_e32 v73, v73
	v_exp_f32_e32 v87, v74
	v_sub_f32_e32 v74, v75, v129
	v_sub_f32_e32 v75, v91, v129
	v_exp_f32_e32 v74, v74
	v_exp_f32_e32 v88, v75
	v_add_f32_e32 v75, v73, v87
	v_cvt_pk_bf16_f32 v71, v73, v74
	v_pk_add_f32 v[90:91], v[74:75], v[88:89]
	v_sub_f32_e32 v75, v76, v129
	v_sub_f32_e32 v76, v92, v129
	v_pk_add_f32 v[90:91], v[90:91], v[90:91] op_sel_hi:[0,1]
	v_exp_f32_e32 v75, v75
	v_exp_f32_e32 v89, v76
	v_sub_f32_e32 v76, v77, v129
	v_sub_f32_e32 v77, v93, v129
	v_exp_f32_e32 v76, v76
	v_exp_f32_e32 v90, v77
	v_add_f32_e32 v77, v75, v89
	v_cvt_pk_bf16_f32 v72, v75, v76
	v_pk_add_f32 v[92:93], v[76:77], v[90:91]
	v_sub_f32_e32 v77, v78, v129
	v_sub_f32_e32 v78, v94, v129
	v_pk_add_f32 v[92:93], v[92:93], v[92:93] op_sel_hi:[0,1]
	v_exp_f32_e32 v77, v77
	v_exp_f32_e32 v91, v78
	v_sub_f32_e32 v78, v79, v129
	v_sub_f32_e32 v79, v95, v129
	v_exp_f32_e32 v78, v78
	v_exp_f32_e32 v92, v79
	v_add_f32_e32 v79, v77, v91
	v_cvt_pk_bf16_f32 v73, v77, v78
	v_pk_add_f32 v[94:95], v[78:79], v[92:93]
	v_sub_f32_e32 v79, v80, v129
	v_sub_f32_e32 v80, v96, v129
	v_pk_add_f32 v[94:95], v[94:95], v[94:95] op_sel_hi:[0,1]
	v_exp_f32_e32 v79, v79
	v_exp_f32_e32 v93, v80
	v_sub_f32_e32 v80, v81, v129
	v_sub_f32_e32 v81, v97, v129
	v_exp_f32_e32 v80, v80
	v_exp_f32_e32 v94, v81
	v_add_f32_e32 v81, v79, v93
	v_cvt_pk_bf16_f32 v74, v79, v80
	v_pk_add_f32 v[96:97], v[80:81], v[94:95]
	v_sub_f32_e32 v81, v82, v129
	v_sub_f32_e32 v82, v98, v129
	v_pk_add_f32 v[96:97], v[96:97], v[96:97] op_sel_hi:[0,1]
	v_exp_f32_e32 v81, v81
	v_exp_f32_e32 v95, v82
	v_sub_f32_e32 v82, v83, v129
	v_sub_f32_e32 v83, v99, v129
	v_exp_f32_e32 v82, v82
	v_exp_f32_e32 v96, v83
	v_add_f32_e32 v83, v81, v95
	v_cvt_pk_bf16_f32 v75, v81, v82
	v_cvt_pk_bf16_f32 v76, v205, v84
	v_pk_add_f32 v[98:99], v[82:83], v[96:97]
	v_cvt_pk_bf16_f32 v77, v85, v202
	v_cvt_pk_bf16_f32 v78, v203, v86
	v_cvt_pk_bf16_f32 v79, v87, v88
	v_cvt_pk_bf16_f32 v80, v89, v90
	v_cvt_pk_bf16_f32 v81, v91, v92
	s_nop 0
	v_add_f32_e32 v83, v98, v99
	v_add_f32_e32 v34, v34, v83
	v_cvt_pk_bf16_f32 v82, v93, v94
	v_cvt_pk_bf16_f32 v83, v95, v96
	s_waitcnt lgkmcnt(0)
	v_mfma_f32_32x32x16_bf16 v[2:17], v[220:223], v[68:71], v[2:17]
	v_mfma_f32_32x32x16_bf16 v[2:17], v[224:227], v[72:75], v[2:17]
	v_mfma_f32_32x32x16_bf16 v[2:17], v[228:231], v[76:79], v[2:17]
	v_mfma_f32_32x32x16_bf16 v[2:17], v[232:235], v[80:83], v[2:17]
	v_mfma_f32_32x32x16_bf16 v[18:33], v[236:239], v[68:71], v[18:33]
	v_mfma_f32_32x32x16_bf16 v[18:33], v[240:243], v[72:75], v[18:33]
	v_mfma_f32_32x32x16_bf16 v[18:33], v[244:247], v[76:79], v[18:33]
	v_mfma_f32_32x32x16_bf16 v[18:33], v[248:251], v[80:83], v[18:33]

; #define LAS __attribute__((address_space(3)))
; __device__ __forceinline__ unsigned pk(float lo, float hi) { return pg8::cvt_pk_bf16(lo, hi); }
; #define MFMA32(a, b, c) __builtin_amdgcn_mfma_f32_32x32x16_bf16((a), (b), (c), 0, 0, 0)
; template <bool QLDS> __device__ __forceinline__ void attn_tile(const LAS unsigned char* buf, const bf16x8 (&qf)[4], const LAS bf16x8* qlds, float cq2, int qpos, int kv0, bool diag, float& mrun, float& lrun, f32x16 (&ot)[2], int l31, int hi) {
;     ...
;     float rs = 0.f;
; #pragma unroll
;     for (int r = 0; r < 16; ++r) { p0[r] = __builtin_amdgcn_exp2f(p0[r] - mrun); p1[r] = __builtin_amdgcn_exp2f(p1[r] - mrun); rs += p0[r] + p1[r]; }
;     lrun += rs;
;     bf16x8 pf[4];
;     { u32x4 x; x.x = pk(p0[0], p0[1]); x.y = pk(p0[2], p0[3]); x.z = pk(p0[4], p0[5]); x.w = pk(p0[6], p0[7]); pf[0] = __builtin_bit_cast(bf16x8, x);
;       x.x = pk(p0[8], p0[9]); x.y = pk(p0[10], p0[11]); x.z = pk(p0[12], p0[13]); x.w = pk(p0[14], p0[15]); pf[1] = __builtin_bit_cast(bf16x8, x);
;       x.x = pk(p1[0], p1[1]); x.y = pk(p1[2], p1[3]); x.z = pk(p1[4], p1[5]); x.w = pk(p1[6], p1[7]); pf[2] = __builtin_bit_cast(bf16x8, x);
;       x.x = pk(p1[8], p1[9]); x.y = pk(p1[10], p1[11]); x.z = pk(p1[12], p1[13]); x.w = pk(p1[14], p1[15]); pf[3] = __builtin_bit_cast(bf16x8, x); }
;     __builtin_amdgcn_sched_barrier(0);
; #pragma unroll
;     for (int db = 0; db < 2; ++db)
; #pragma unroll
;         for (int ks = 0; ks < 4; ++ks) { const LAS bf16_t* vp = VTs + (32 * db + l31) * AT_VS + 16 * ks + 4 * hi;
;             const u32x2 lo = *(const LAS u32x2*)vp, hh2 = *(const LAS u32x2*)(vp + 8);
;             u32x4 x; x.x = lo.x; x.y = lo.y; x.z = hh2.x; x.w = hh2.y;
;             ot[db] = MFMA32(__builtin_bit_cast(bf16x8, x), pf[ks], ot[db]); }
.LBB0_1742:
	v_add3_u32 v217, s70, v147, v199
	v_add_u32_e32 v218, 0x2000, v217
	v_add_u32_e32 v217, 0x3000, v217
	ds_read2_b64 v[220:223], v218 offset0:128 offset1:130
	ds_read2_b64 v[224:227], v218 offset0:132 offset1:134
	ds_read2_b64 v[228:231], v218 offset0:136 offset1:138
	ds_read2_b64 v[232:235], v218 offset0:140 offset1:142
	ds_read2_b64 v[236:239], v217 offset0:160 offset1:162
	ds_read2_b64 v[240:243], v217 offset0:164 offset1:166
	ds_read2_b64 v[244:247], v217 offset0:168 offset1:170
	ds_read2_b64 v[248:251], v217 offset0:172 offset1:174
	v_sub_f32_e32 v68, v68, v129
	v_exp_f32_e32 v206, v68
	v_sub_f32_e32 v68, v84, v129
	v_exp_f32_e32 v207, v68
	v_sub_f32_e32 v68, v69, v129
	v_sub_f32_e32 v69, v85, v129
	v_exp_f32_e32 v68, v68
	v_exp_f32_e32 v84, v69
	v_add_f32_e32 v69, v206, v207
	v_mov_b32_e32 v85, v67
	v_pk_add_f32 v[204:205], v[68:69], v[84:85]
	v_sub_f32_e32 v69, v70, v129
	v_sub_f32_e32 v70, v86, v129
	v_pk_add_f32 v[204:205], v[204:205], v[204:205] op_sel_hi:[0,1]
	v_exp_f32_e32 v69, v69
	v_exp_f32_e32 v85, v70
	v_sub_f32_e32 v70, v71, v129
	v_sub_f32_e32 v71, v87, v129
	v_exp_f32_e32 v70, v70
	v_exp_f32_e32 v204, v71
	v_add_f32_e32 v71, v69, v85
	v_cvt_pk_bf16_f32 v68, v206, v68
	v_cvt_pk_bf16_f32 v69, v69, v70
	v_pk_add_f32 v[86:87], v[70:71], v[204:205]
	v_sub_f32_e32 v71, v72, v129
	v_sub_f32_e32 v72, v88, v129
	v_pk_add_f32 v[86:87], v[86:87], v[86:87] op_sel_hi:[0,1]
	v_exp_f32_e32 v71, v71
	v_exp_f32_e32 v205, v72
	v_sub_f32_e32 v72, v73, v129
	v_sub_f32_e32 v73, v89, v129
	v_exp_f32_e32 v72, v72
	v_exp_f32_e32 v86, v73
	v_add_f32_e32 v73, v71, v205
	v_cvt_pk_bf16_f32 v70, v71, v72
	v_pk_add_f32 v[88:89], v[72:73], v[86:87]
	v_sub_f32_e32 v73, v74, v129
	v_sub_f32_e32 v74, v90, v129
	v_pk_add_f32 v[88:89], v[88:89], v[88:89] op_sel_hi:[0,1]
	v_exp_f32_e32 v73, v73
	v_exp_f32_e32 v87, v74
	v_sub_f32_e32 v74, v75, v129
	v_sub_f32_e32 v75, v91, v129
	v_exp_f32_e32 v74, v74
	v_exp_f32_e32 v88, v75
	v_add_f32_e32 v75, v73, v87
	v_cvt_pk_bf16_f32 v71, v73, v74
	v_pk_add_f32 v[90:91], v[74:75], v[88:89]
	v_sub_f32_e32 v75, v76, v129
	v_sub_f32_e32 v76, v92, v129
	v_pk_add_f32 v[90:91], v[90:91], v[90:91] op_sel_hi:[0,1]
	v_exp_f32_e32 v75, v75
	v_exp_f32_e32 v89, v76
	v_sub_f32_e32 v76, v77, v129
	v_sub_f32_e32 v77, v93, v129
	v_exp_f32_e32 v76, v76
	v_exp_f32_e32 v90, v77
	v_add_f32_e32 v77, v75, v89
	v_cvt_pk_bf16_f32 v72, v75, v76
	v_pk_add_f32 v[92:93], v[76:77], v[90:91]
	v_sub_f32_e32 v77, v78, v129
	v_sub_f32_e32 v78, v94, v129
	v_pk_add_f32 v[92:93], v[92:93], v[92:93] op_sel_hi:[0,1]
	v_exp_f32_e32 v77, v77
	v_exp_f32_e32 v91, v78
	v_sub_f32_e32 v78, v79, v129
	v_sub_f32_e32 v79, v95, v129
	v_exp_f32_e32 v78, v78
	v_exp_f32_e32 v92, v79
	v_add_f32_e32 v79, v77, v91
	v_cvt_pk_bf16_f32 v73, v77, v78
	v_pk_add_f32 v[94:95], v[78:79], v[92:93]
	v_sub_f32_e32 v79, v80, v129
	v_sub_f32_e32 v80, v96, v129
	v_pk_add_f32 v[94:95], v[94:95], v[94:95] op_sel_hi:[0,1]
	v_exp_f32_e32 v79, v79
	v_exp_f32_e32 v93, v80
	v_sub_f32_e32 v80, v81, v129
	v_sub_f32_e32 v81, v97, v129
	v_exp_f32_e32 v80, v80
	v_exp_f32_e32 v94, v81
	v_add_f32_e32 v81, v79, v93
	v_cvt_pk_bf16_f32 v74, v79, v80
	v_pk_add_f32 v[96:97], v[80:81], v[94:95]
	v_sub_f32_e32 v81, v82, v129
	v_sub_f32_e32 v82, v98, v129
	v_pk_add_f32 v[96:97], v[96:97], v[96:97] op_sel_hi:[0,1]
	v_exp_f32_e32 v81, v81
	v_exp_f32_e32 v95, v82
	v_sub_f32_e32 v82, v83, v129
	v_sub_f32_e32 v83, v99, v129
	v_exp_f32_e32 v82, v82
	v_exp_f32_e32 v96, v83
	v_add_f32_e32 v83, v81, v95
	v_cvt_pk_bf16_f32 v75, v81, v82
	v_cvt_pk_bf16_f32 v76, v207, v84
	v_pk_add_f32 v[98:99], v[82:83], v[96:97]
	v_cvt_pk_bf16_f32 v77, v85, v204
	v_cvt_pk_bf16_f32 v78, v205, v86
	v_cvt_pk_bf16_f32 v79, v87, v88
	v_cvt_pk_bf16_f32 v80, v89, v90
	v_cvt_pk_bf16_f32 v81, v91, v92
	s_nop 0
	v_add_f32_e32 v83, v98, v99
	v_add_f32_e32 v34, v34, v83
	v_cvt_pk_bf16_f32 v82, v93, v94
	v_cvt_pk_bf16_f32 v83, v95, v96
	s_waitcnt lgkmcnt(0)
	v_mfma_f32_32x32x16_bf16 v[2:17], v[220:223], v[68:71], v[2:17]
	v_mfma_f32_32x32x16_bf16 v[2:17], v[224:227], v[72:75], v[2:17]
	v_mfma_f32_32x32x16_bf16 v[2:17], v[228:231], v[76:79], v[2:17]
	v_mfma_f32_32x32x16_bf16 v[2:17], v[232:235], v[80:83], v[2:17]
	v_mfma_f32_32x32x16_bf16 v[18:33], v[236:239], v[68:71], v[18:33]
	v_mfma_f32_32x32x16_bf16 v[18:33], v[240:243], v[72:75], v[18:33]
	v_mfma_f32_32x32x16_bf16 v[18:33], v[244:247], v[76:79], v[18:33]
	v_mfma_f32_32x32x16_bf16 v[18:33], v[248:251], v[80:83], v[18:33]
